# resid_norm row loops software-pipelined across rows (next row's 16 loads in flight during the current row), x2 unroll with two register sets
# baseline (speedup 1.0000x reference)
; DI int get_tid() { int t = threadIdx.x; asm volatile("" : "+v"(t)); return t; }
; DI int get_bid() { int b = blockIdx.x; asm volatile("" : "+s"(b)); return b; }
; DI float bflo(unsigned u) { return __uint_as_float(u << 16); }
; DI float bfhi(unsigned u) { return __uint_as_float(u & 0xffff0000u); }
; DI void resid_norm(const Params& p, int layer, const u16* __restrict__ y) {
;     ...
;   for (int r = get_bid() * 4 + (get_tid() >> 6); r < M_TOK; r += gridDim.x * 4) {
;     const float* x;
;     if (layer == 0) x = r < M_PROMPT ? p.x_prompt + (size_t)r * 1024 : p.x_sample + (size_t)(r - M_PROMPT) * 1024;
;     else x = p.out + (size_t)r * 1024;
;     float4 yv[4], xv[4]; float ss = 0.f;
; #pragma unroll
;     for (int i = 0; i < 4; ++i) {
;       { const uint2 yq = *(const uint2*)(y + (size_t)r * 1024 + lane * 4 + 256 * i); yv[i] = make_float4(bflo(yq.x), bfhi(yq.x), bflo(yq.y), bfhi(yq.y)); }
;       { const f32x4 t4 = __builtin_nontemporal_load((const f32x4*)(x + lane * 4 + 256 * i)); xv[i] = make_float4(t4[0], t4[1], t4[2], t4[3]); }
;       ss += yv[i].x * yv[i].x + yv[i].y * yv[i].y + yv[i].z * yv[i].z + yv[i].w * yv[i].w;
;     }
;     ss = wave_sum(ss);
;     const float rs = rsqrtf(ss * (1.f / 1024.f) + 1e-6f);
; DI void run_phase(const Params& p, int ph, char* smem) {
;   if (ph == 0) { convert_weights(p, 0, smem); prenorm0(p); }
;   else if (ph <= 5) phase_even(p, 0, ph - 1, smem);
;   else if (ph <= 12) phase_odd(p, 0, ph - 6, smem);
;   else if (ph <= 17) phase_even(p, 1, ph - 13, smem);
;   else phase_odd(p, 1, ph - 18, smem);
.LBB0_12:
	v_readlane_b32 s4, v255, 27
	s_cmp_gt_u32 s4, 17
	s_cbranch_scc0 .LBB0_24
	s_cmp_lt_i32 s4, 21
	s_cbranch_scc1 .LBB0_34
	s_cmp_gt_i32 s4, 21
	s_cbranch_scc0 .LBB0_35
	s_cmp_gt_i32 s4, 22
	s_cbranch_scc0 .LBB0_37
	v_readlane_b32 s4, v255, 27
	s_cmp_lg_u32 s4, 23
	s_cbranch_scc0 .LBB0_21
	v_mov_b32_e32 v1, v185
	s_mov_b32 s4, s2
	v_mov_b32_e32 v0, v185
	s_nop 0
	v_ashrrev_i32_e32 v0, 6, v0
	v_lshl_add_u32 v0, s4, 2, v0
	s_movk_i32 s4, 0x4200
	v_cmp_gt_i32_e32 vcc, s4, v0
	s_and_saveexec_b64 s[38:39], vcc
	s_cbranch_execz .LBB0_20
	v_cmp_lt_i32_e32 vcc, v206, v205
	v_lshlrev_b32_e32 v1, 2, v1
	v_and_b32_e32 v1, 0xfc, v1
	v_cndmask_b32_e32 v4, v204, v206, vcc
	v_cmp_lt_i32_e32 vcc, v207, v205
	v_lshlrev_b32_e32 v8, 2, v4
	v_lshlrev_b32_e32 v182, 1, v1
	v_cndmask_b32_e32 v4, v204, v207, vcc
	v_cmp_lt_i32_e32 vcc, v208, v205
	v_lshlrev_b32_e32 v9, 2, v4
	v_readlane_b32 s4, v252, 31
	v_cndmask_b32_e32 v4, v204, v208, vcc
	v_cmp_lt_i32_e32 vcc, v209, v205
	v_lshlrev_b32_e32 v10, 2, v4
	v_lshl_add_u64 v[2:3], s[92:93], 0, v[182:183]
	v_cndmask_b32_e32 v4, v204, v209, vcc
	v_cmp_lt_i32_e32 vcc, v210, v205
	v_lshlrev_b32_e32 v11, 2, v4
	v_lshlrev_b32_e32 v182, 2, v1
	v_cndmask_b32_e32 v4, v204, v210, vcc
	v_cmp_lt_i32_e32 vcc, v211, v205
	v_lshlrev_b32_e32 v12, 2, v4
	v_readlane_b32 s5, v252, 32
	v_cndmask_b32_e32 v4, v204, v211, vcc
	v_lshlrev_b32_e32 v13, 2, v4
	v_lshl_add_u64 v[4:5], s[4:5], 0, v[182:183]
	v_readlane_b32 s4, v255, 5
	v_readlane_b32 s6, v255, 7
	v_readlane_b32 s7, v255, 8
	s_mov_b64 s[40:41], 0
	v_readlane_b32 s5, v255, 6
	v_lshl_add_u64 v[6:7], s[6:7], 0, v[182:183]
	v_readlane_b32 s8, v255, 9
	v_readlane_b32 s9, v255, 10
	v_readlane_b32 s10, v255, 11
	v_readlane_b32 s11, v255, 12
	v_ashrrev_i32_e32 v140, 31, v0
	v_mov_b32_e32 v194, v0
	v_mov_b32_e32 v195, v140
	v_lshlrev_b64 v[142:143], 11, v[194:195]
	v_lshl_add_u64 v[144:145], v[2:3], 0, v[142:143]
	global_load_dwordx2 v[146:147], v[144:145], off
	global_load_dwordx2 v[148:149], v[144:145], off offset:512
	global_load_dwordx2 v[150:151], v[144:145], off offset:1024
	global_load_dwordx2 v[152:153], v[144:145], off offset:1536
	global_load_dwordx4 v[154:157], v[4:5], off
	v_mov_b32_e32 v196, v0
	v_mov_b32_e32 v197, v140
	v_lshlrev_b64 v[158:159], 12, v[196:197]
	v_lshl_add_u64 v[160:161], v[6:7], 0, v[158:159]
	global_load_dwordx4 v[162:165], v[160:161], off nt
	global_load_dwordx4 v[166:169], v[160:161], off offset:1024 nt
	global_load_dwordx4 v[170:173], v[4:5], off offset:1024
	global_load_dwordx4 v[174:177], v[4:5], off offset:2048
	global_load_dwordx4 v[178:181], v[160:161], off offset:2048 nt
	global_load_dwordx4 v[186:189], v[160:161], off offset:3072 nt
	global_load_dwordx4 v[190:193], v[4:5], off offset:3072
	s_waitcnt vmcnt(0)
.LBB0_19:
	v_add_u32_e32 v65, s3, v0
	v_min_i32_e32 v65, s64, v65
	v_ashrrev_i32_e32 v64, 31, v65
	v_mov_b32_e32 v114, v65
	v_mov_b32_e32 v115, v64
	v_lshlrev_b64 v[66:67], 11, v[114:115]
	v_lshl_add_u64 v[68:69], v[2:3], 0, v[66:67]
	global_load_dwordx2 v[70:71], v[68:69], off
	global_load_dwordx2 v[72:73], v[68:69], off offset:512
	global_load_dwordx2 v[74:75], v[68:69], off offset:1024
	global_load_dwordx2 v[76:77], v[68:69], off offset:1536
	global_load_dwordx4 v[78:81], v[4:5], off
	v_mov_b32_e32 v116, v65
	v_mov_b32_e32 v117, v64
	v_lshlrev_b64 v[82:83], 12, v[116:117]
	v_lshl_add_u64 v[84:85], v[6:7], 0, v[82:83]
	global_load_dwordx4 v[86:89], v[84:85], off nt
	global_load_dwordx4 v[90:93], v[84:85], off offset:1024 nt
	global_load_dwordx4 v[94:97], v[4:5], off offset:1024
	global_load_dwordx4 v[98:101], v[4:5], off offset:2048
	global_load_dwordx4 v[102:105], v[84:85], off offset:2048 nt
	global_load_dwordx4 v[106:109], v[84:85], off offset:3072 nt
	global_load_dwordx4 v[110:113], v[4:5], off offset:3072
	s_nop 0
	s_nop 0
	s_nop 0
	s_nop 0
	s_nop 0
	s_nop 0
	s_nop 0
	s_nop 0
	s_nop 0
	s_waitcnt vmcnt(16)
	s_nop 0
	s_waitcnt vmcnt(16)
	s_nop 0
	s_nop 0
	v_add_u32_e32 v0, s3, v0
	s_waitcnt vmcnt(16)
	v_and_b32_e32 v33, 0xffff0000, v146
	v_lshlrev_b32_e32 v32, 16, v146
	s_waitcnt vmcnt(16)
	v_and_b32_e32 v39, 0xffff0000, v148
	s_waitcnt vmcnt(16)
	v_and_b32_e32 v45, 0xffff0000, v150
	v_mov_b32_e32 v38, v33
	v_lshlrev_b32_e32 v34, 16, v147
	v_and_b32_e32 v35, 0xffff0000, v147
	v_lshlrev_b32_e32 v37, 16, v148
	v_lshlrev_b32_e32 v44, 16, v150
	s_waitcnt vmcnt(16)
	v_and_b32_e32 v49, 0xffff0000, v152
	v_mov_b32_e32 v36, v32
	v_mov_b32_e32 v48, v45
	v_pk_mul_f32 v[22:23], v[38:39], v[38:39]
	v_lshlrev_b32_e32 v41, 16, v149
	v_and_b32_e32 v43, 0xffff0000, v149
	v_lshlrev_b32_e32 v26, 16, v151
	v_lshlrev_b32_e32 v47, 16, v152
	v_mov_b32_e32 v40, v34
	v_mov_b32_e32 v46, v44
	v_pk_mul_f32 v[24:25], v[48:49], v[48:49]
	v_pk_fma_f32 v[22:23], v[36:37], v[36:37], v[22:23]
	v_and_b32_e32 v27, 0xffff0000, v151
	v_lshlrev_b32_e32 v51, 16, v153
	v_mov_b32_e32 v42, v35
	v_mov_b32_e32 v50, v26
	v_pk_fma_f32 v[24:25], v[46:47], v[46:47], v[24:25]
	v_pk_fma_f32 v[22:23], v[40:41], v[40:41], v[22:23]
	v_and_b32_e32 v29, 0xffff0000, v153
	v_mov_b32_e32 v28, v27
	v_pk_fma_f32 v[24:25], v[50:51], v[50:51], v[24:25]
	v_pk_fma_f32 v[22:23], v[42:43], v[42:43], v[22:23]
	v_pk_fma_f32 v[24:25], v[28:29], v[28:29], v[24:25]
	v_add_f32_e32 v1, v22, v23
	v_add_f32_e32 v1, v1, v24
	v_add_f32_e32 v1, v1, v25
	v_mov_b32_e32 v22, v1
	s_nop 1
	v_permlane32_swap_b32_e32 v1, v22
	v_mov_b32_e32 v38, v37
	v_mov_b32_e32 v42, v41
	v_mov_b32_e32 v48, v47
	s_waitcnt lgkmcnt(0)
	v_add_f32_e32 v1, v1, v22
	v_mov_b32_e32 v22, v1
	s_nop 1
	v_permlane16_swap_b32_e32 v1, v22
	s_waitcnt lgkmcnt(0)
	v_add_f32_e32 v1, v1, v22
	s_nop 1
	v_mov_b32_dpp v22, v1 row_ror:8 row_mask:0xf bank_mask:0xf
	s_waitcnt lgkmcnt(0)
; DI void resid_norm(const Params& p, int layer, const u16* __restrict__ y) {
;     ...
;     ss = wave_sum(ss);
;     const float rs = rsqrtf(ss * (1.f / 1024.f) + 1e-6f);
;     float ss2 = 0.f;
; #pragma unroll
;     for (int i = 0; i < 4; ++i) {
;       const float4 gg = *(const float4*)(gpost + lane * 4 + 256 * i);
;       xv[i].x += yv[i].x * rs * gg.x; xv[i].y += yv[i].y * rs * gg.y; xv[i].z += yv[i].z * rs * gg.z; xv[i].w += yv[i].w * rs * gg.w;
;       __builtin_nontemporal_store((f32x4){xv[i].x, xv[i].y, xv[i].z, xv[i].w}, (f32x4*)(p.out + (size_t)r * 1024 + lane * 4 + 256 * i));
;       ss2 += xv[i].x * xv[i].x + xv[i].y * xv[i].y + xv[i].z * xv[i].z + xv[i].w * xv[i].w;
;     }
	v_add_f32_e32 v1, v1, v22
	s_nop 1
	v_mov_b32_dpp v22, v1 row_ror:4 row_mask:0xf bank_mask:0xf
	s_waitcnt lgkmcnt(0)
	v_add_f32_e32 v1, v1, v22
	s_nop 1
	v_mov_b32_dpp v22, v1 quad_perm:[2,3,0,1] row_mask:0xf bank_mask:0xf
	s_waitcnt lgkmcnt(0)
	v_add_f32_e32 v1, v1, v22
	s_nop 1
	v_mov_b32_dpp v22, v1 quad_perm:[1,0,3,2] row_mask:0xf bank_mask:0xf
	s_waitcnt lgkmcnt(0)
	v_add_f32_e32 v1, v1, v22
	v_fmamk_f32 v1, v1, 0x3a800000, v184
	v_mul_f32_e32 v22, 0x4b800000, v1
	v_cmp_gt_f32_e32 vcc, s33, v1
	s_nop 1
	v_cndmask_b32_e32 v1, v1, v22, vcc
	v_rsq_f32_e32 v1, v1
	s_nop 0
	v_mul_f32_e32 v28, 0x45800000, v1
	v_cndmask_b32_e32 v36, v1, v28, vcc
	v_pk_mul_f32 v[32:33], v[36:37], v[32:33] op_sel_hi:[0,1]
	v_pk_mul_f32 v[34:35], v[36:37], v[34:35] op_sel_hi:[0,1]
	s_waitcnt vmcnt(16)
	v_pk_fma_f32 v[16:17], v[156:157], v[34:35], v[164:165]
	v_pk_fma_f32 v[14:15], v[154:155], v[32:33], v[162:163]
	global_store_dwordx4 v[160:161], v[14:17], off nt
	s_nop 0
	v_pk_mul_f32 v[18:19], v[36:37], v[42:43] op_sel_hi:[0,1]
	v_pk_mul_f32 v[20:21], v[36:37], v[38:39] op_sel_hi:[0,1]
	v_pk_mul_f32 v[32:33], v[36:37], v[44:45] op_sel_hi:[0,1]
	v_pk_mul_f32 v[26:27], v[36:37], v[26:27] op_sel_hi:[0,1]
	v_mov_b32_e32 v28, v51
	v_cmp_lt_i32_e32 vcc, s64, v0
	s_or_b64 s[40:41], vcc, s[40:41]
	s_waitcnt vmcnt(17)
	v_pk_fma_f32 v[14:15], v[170:171], v[20:21], v[166:167]
	v_pk_fma_f32 v[16:17], v[172:173], v[18:19], v[168:169]
	global_store_dwordx4 v[160:161], v[14:17], off offset:1024 nt
	s_nop 0
	s_nop 0
	s_nop 0
	s_nop 0
	s_waitcnt vmcnt(18)
	v_pk_fma_f32 v[14:15], v[174:175], v[32:33], v[178:179]
	v_pk_fma_f32 v[16:17], v[26:27], v[176:177], v[180:181]
	global_store_dwordx4 v[160:161], v[14:17], off offset:2048 nt
	s_nop 0
	v_pk_mul_f32 v[18:19], v[36:37], v[28:29] op_sel_hi:[0,1]
	v_pk_mul_f32 v[20:21], v[36:37], v[48:49] op_sel_hi:[0,1]
	s_waitcnt vmcnt(16)
	v_pk_fma_f32 v[14:15], v[20:21], v[190:191], v[186:187]
	v_pk_fma_f32 v[16:17], v[18:19], v[192:193], v[188:189]
	global_store_dwordx4 v[160:161], v[14:17], off offset:3072 nt
	v_mov_b32_e32 v22, v186
	v_mov_b32_e32 v23, v187
	v_mov_b32_e32 v24, v188
	v_mov_b32_e32 v25, v189
	v_mov_b32_e32 v30, v160
	v_mov_b32_e32 v31, v161
	s_andn2_b64 exec, exec, s[40:41]
	s_cbranch_execz .Lrnp_exit_2
; DI int get_tid() { int t = threadIdx.x; asm volatile("" : "+v"(t)); return t; }
; DI int get_bid() { int b = blockIdx.x; asm volatile("" : "+s"(b)); return b; }
; DI float bflo(unsigned u) { return __uint_as_float(u << 16); }
; DI float bfhi(unsigned u) { return __uint_as_float(u & 0xffff0000u); }
; DI void resid_norm(const Params& p, int layer, const u16* __restrict__ y) {
;     ...
;   for (int r = get_bid() * 4 + (get_tid() >> 6); r < M_TOK; r += gridDim.x * 4) {
;     const float* x;
;     if (layer == 0) x = r < M_PROMPT ? p.x_prompt + (size_t)r * 1024 : p.x_sample + (size_t)(r - M_PROMPT) * 1024;
;     else x = p.out + (size_t)r * 1024;
;     float4 yv[4], xv[4]; float ss = 0.f;
; #pragma unroll
;     for (int i = 0; i < 4; ++i) {
;       { const uint2 yq = *(const uint2*)(y + (size_t)r * 1024 + lane * 4 + 256 * i); yv[i] = make_float4(bflo(yq.x), bfhi(yq.x), bflo(yq.y), bfhi(yq.y)); }
;       { const f32x4 t4 = __builtin_nontemporal_load((const f32x4*)(x + lane * 4 + 256 * i)); xv[i] = make_float4(t4[0], t4[1], t4[2], t4[3]); }
;       ss += yv[i].x * yv[i].x + yv[i].y * yv[i].y + yv[i].z * yv[i].z + yv[i].w * yv[i].w;
;     }
;     ss = wave_sum(ss);
;     const float rs = rsqrtf(ss * (1.f / 1024.f) + 1e-6f);
;     float ss2 = 0.f;
; #pragma unroll
;     for (int i = 0; i < 4; ++i) {
;       const float4 gg = *(const float4*)(gpost + lane * 4 + 256 * i);
;       xv[i].x += yv[i].x * rs * gg.x; xv[i].y += yv[i].y * rs * gg.y; xv[i].z += yv[i].z * rs * gg.z; xv[i].w += yv[i].w * rs * gg.w;
;       __builtin_nontemporal_store((f32x4){xv[i].x, xv[i].y, xv[i].z, xv[i].w}, (f32x4*)(p.out + (size_t)r * 1024 + lane * 4 + 256 * i));
;       ss2 += xv[i].x * xv[i].x + xv[i].y * xv[i].y + xv[i].z * xv[i].z + xv[i].w * xv[i].w;
;     }
	v_add_u32_e32 v65, s3, v0
	v_min_i32_e32 v65, s64, v65
	v_ashrrev_i32_e32 v140, 31, v65
	v_mov_b32_e32 v194, v65
	v_mov_b32_e32 v195, v140
	v_lshlrev_b64 v[142:143], 11, v[194:195]
	v_lshl_add_u64 v[144:145], v[2:3], 0, v[142:143]
	global_load_dwordx2 v[146:147], v[144:145], off
	global_load_dwordx2 v[148:149], v[144:145], off offset:512
	global_load_dwordx2 v[150:151], v[144:145], off offset:1024
	global_load_dwordx2 v[152:153], v[144:145], off offset:1536
	global_load_dwordx4 v[154:157], v[4:5], off
	v_mov_b32_e32 v196, v65
	v_mov_b32_e32 v197, v140
	v_lshlrev_b64 v[158:159], 12, v[196:197]
	v_lshl_add_u64 v[160:161], v[6:7], 0, v[158:159]
	global_load_dwordx4 v[162:165], v[160:161], off nt
	global_load_dwordx4 v[166:169], v[160:161], off offset:1024 nt
	global_load_dwordx4 v[170:173], v[4:5], off offset:1024
	global_load_dwordx4 v[174:177], v[4:5], off offset:2048
	global_load_dwordx4 v[178:181], v[160:161], off offset:2048 nt
	global_load_dwordx4 v[186:189], v[160:161], off offset:3072 nt
	global_load_dwordx4 v[190:193], v[4:5], off offset:3072
	s_nop 0
	s_nop 0
	s_nop 0
	s_nop 0
	s_nop 0
	s_nop 0
	s_nop 0
	s_nop 0
	s_nop 0
	s_waitcnt vmcnt(16)
	s_nop 0
	s_waitcnt vmcnt(16)
	s_nop 0
	s_nop 0
	v_add_u32_e32 v0, s3, v0
	s_waitcnt vmcnt(16)
	v_and_b32_e32 v33, 0xffff0000, v70
	v_lshlrev_b32_e32 v32, 16, v70
	s_waitcnt vmcnt(16)
	v_and_b32_e32 v39, 0xffff0000, v72
	s_waitcnt vmcnt(16)
	v_and_b32_e32 v45, 0xffff0000, v74
	v_mov_b32_e32 v38, v33
	v_lshlrev_b32_e32 v34, 16, v71
	v_and_b32_e32 v35, 0xffff0000, v71
	v_lshlrev_b32_e32 v37, 16, v72
	v_lshlrev_b32_e32 v44, 16, v74
	s_waitcnt vmcnt(16)
	v_and_b32_e32 v49, 0xffff0000, v76
	v_mov_b32_e32 v36, v32
	v_mov_b32_e32 v48, v45
	v_pk_mul_f32 v[22:23], v[38:39], v[38:39]
	v_lshlrev_b32_e32 v41, 16, v73
	v_and_b32_e32 v43, 0xffff0000, v73
	v_lshlrev_b32_e32 v26, 16, v75
	v_lshlrev_b32_e32 v47, 16, v76
	v_mov_b32_e32 v40, v34
	v_mov_b32_e32 v46, v44
	v_pk_mul_f32 v[24:25], v[48:49], v[48:49]
	v_pk_fma_f32 v[22:23], v[36:37], v[36:37], v[22:23]
	v_and_b32_e32 v27, 0xffff0000, v75
	v_lshlrev_b32_e32 v51, 16, v77
	v_mov_b32_e32 v42, v35
	v_mov_b32_e32 v50, v26
	v_pk_fma_f32 v[24:25], v[46:47], v[46:47], v[24:25]
	v_pk_fma_f32 v[22:23], v[40:41], v[40:41], v[22:23]
	v_and_b32_e32 v29, 0xffff0000, v77
	v_mov_b32_e32 v28, v27
	v_pk_fma_f32 v[24:25], v[50:51], v[50:51], v[24:25]
	v_pk_fma_f32 v[22:23], v[42:43], v[42:43], v[22:23]
	v_pk_fma_f32 v[24:25], v[28:29], v[28:29], v[24:25]
	v_add_f32_e32 v1, v22, v23
	v_add_f32_e32 v1, v1, v24
	v_add_f32_e32 v1, v1, v25
	v_mov_b32_e32 v22, v1
	s_nop 1
	v_permlane32_swap_b32_e32 v1, v22
	v_mov_b32_e32 v38, v37
	v_mov_b32_e32 v42, v41
	v_mov_b32_e32 v48, v47
	s_waitcnt lgkmcnt(0)
	v_add_f32_e32 v1, v1, v22
	v_mov_b32_e32 v22, v1
	s_nop 1
	v_permlane16_swap_b32_e32 v1, v22
	s_waitcnt lgkmcnt(0)
	v_add_f32_e32 v1, v1, v22
	s_nop 1
	v_mov_b32_dpp v22, v1 row_ror:8 row_mask:0xf bank_mask:0xf
	s_waitcnt lgkmcnt(0)
	v_add_f32_e32 v1, v1, v22
	s_nop 1
	v_mov_b32_dpp v22, v1 row_ror:4 row_mask:0xf bank_mask:0xf
	s_waitcnt lgkmcnt(0)
	v_add_f32_e32 v1, v1, v22
	s_nop 1
	v_mov_b32_dpp v22, v1 quad_perm:[2,3,0,1] row_mask:0xf bank_mask:0xf
	s_waitcnt lgkmcnt(0)
	v_add_f32_e32 v1, v1, v22
	s_nop 1
	v_mov_b32_dpp v22, v1 quad_perm:[1,0,3,2] row_mask:0xf bank_mask:0xf
	s_waitcnt lgkmcnt(0)
	v_add_f32_e32 v1, v1, v22
	v_fmamk_f32 v1, v1, 0x3a800000, v184
	v_mul_f32_e32 v22, 0x4b800000, v1
	v_cmp_gt_f32_e32 vcc, s33, v1
	s_nop 1
	v_cndmask_b32_e32 v1, v1, v22, vcc
	v_rsq_f32_e32 v1, v1
	s_nop 0
	v_mul_f32_e32 v28, 0x45800000, v1
	v_cndmask_b32_e32 v36, v1, v28, vcc
	v_pk_mul_f32 v[32:33], v[36:37], v[32:33] op_sel_hi:[0,1]
	v_pk_mul_f32 v[34:35], v[36:37], v[34:35] op_sel_hi:[0,1]
	s_waitcnt vmcnt(16)
	v_pk_fma_f32 v[16:17], v[80:81], v[34:35], v[88:89]
	v_pk_fma_f32 v[14:15], v[78:79], v[32:33], v[86:87]
	global_store_dwordx4 v[84:85], v[14:17], off nt
	s_nop 0
	v_pk_mul_f32 v[18:19], v[36:37], v[42:43] op_sel_hi:[0,1]
	v_pk_mul_f32 v[20:21], v[36:37], v[38:39] op_sel_hi:[0,1]
	v_pk_mul_f32 v[32:33], v[36:37], v[44:45] op_sel_hi:[0,1]
	v_pk_mul_f32 v[26:27], v[36:37], v[26:27] op_sel_hi:[0,1]
	v_mov_b32_e32 v28, v51
	v_cmp_lt_i32_e32 vcc, s64, v0
	s_or_b64 s[40:41], vcc, s[40:41]
	s_waitcnt vmcnt(17)
	v_pk_fma_f32 v[14:15], v[94:95], v[20:21], v[90:91]
	v_pk_fma_f32 v[16:17], v[96:97], v[18:19], v[92:93]
	global_store_dwordx4 v[84:85], v[14:17], off offset:1024 nt
	s_nop 0
	s_nop 0
	s_nop 0
	s_nop 0
	s_waitcnt vmcnt(18)
	v_pk_fma_f32 v[14:15], v[98:99], v[32:33], v[102:103]
	v_pk_fma_f32 v[16:17], v[26:27], v[100:101], v[104:105]
	global_store_dwordx4 v[84:85], v[14:17], off offset:2048 nt
	s_nop 0
	v_pk_mul_f32 v[18:19], v[36:37], v[28:29] op_sel_hi:[0,1]
	v_pk_mul_f32 v[20:21], v[36:37], v[48:49] op_sel_hi:[0,1]
	s_waitcnt vmcnt(16)
	v_pk_fma_f32 v[14:15], v[20:21], v[110:111], v[106:107]
	v_pk_fma_f32 v[16:17], v[18:19], v[112:113], v[108:109]
	global_store_dwordx4 v[84:85], v[14:17], off offset:3072 nt
	v_mov_b32_e32 v22, v106
	v_mov_b32_e32 v23, v107
	v_mov_b32_e32 v24, v108
	v_mov_b32_e32 v25, v109
	v_mov_b32_e32 v30, v84
	v_mov_b32_e32 v31, v85
	s_andn2_b64 exec, exec, s[40:41]
	s_cbranch_execnz .LBB0_19
.Lrnp_exit_2:
	s_waitcnt vmcnt(0)
.LBB0_20:
	s_or_b64 exec, exec, s[38:39]
	s_mov_b64 s[38:39], 0

; DI int get_tid() { int t = threadIdx.x; asm volatile("" : "+v"(t)); return t; }
; DI int get_bid() { int b = blockIdx.x; asm volatile("" : "+s"(b)); return b; }
; DI float bflo(unsigned u) { return __uint_as_float(u << 16); }
; DI float bfhi(unsigned u) { return __uint_as_float(u & 0xffff0000u); }
; DI void resid_norm(const Params& p, int layer, const u16* __restrict__ y) {
;   const int lane = get_tid() & 63;
;   u16* h = (u16*)(p.ws + OFF_H);
;   const float* gpost = p.norm_post + layer * 1024;
;   const float* gpre = p.norm_pre + (layer + 1) * 1024;
;   for (int r = get_bid() * 4 + (get_tid() >> 6); r < M_TOK; r += gridDim.x * 4) {
;     const float* x;
;     if (layer == 0) x = r < M_PROMPT ? p.x_prompt + (size_t)r * 1024 : p.x_sample + (size_t)(r - M_PROMPT) * 1024;
;     else x = p.out + (size_t)r * 1024;
;     float4 yv[4], xv[4]; float ss = 0.f;
; #pragma unroll
;     for (int i = 0; i < 4; ++i) {
;       { const uint2 yq = *(const uint2*)(y + (size_t)r * 1024 + lane * 4 + 256 * i); yv[i] = make_float4(bflo(yq.x), bfhi(yq.x), bflo(yq.y), bfhi(yq.y)); }
;       { const f32x4 t4 = __builtin_nontemporal_load((const f32x4*)(x + lane * 4 + 256 * i)); xv[i] = make_float4(t4[0], t4[1], t4[2], t4[3]); }
;       ss += yv[i].x * yv[i].x + yv[i].y * yv[i].y + yv[i].z * yv[i].z + yv[i].w * yv[i].w;
; DI void run_phase(const Params& p, int ph, char* smem) {
;   if (ph == 0) { convert_weights(p, 0, smem); prenorm0(p); }
;   else if (ph <= 5) phase_even(p, 0, ph - 1, smem);
;   else if (ph <= 12) phase_odd(p, 0, ph - 6, smem);
;   else if (ph <= 17) phase_even(p, 1, ph - 13, smem);
.LBB0_244:
	v_readlane_b32 s4, v255, 27
	s_cmp_lt_i32 s4, 15
	s_mov_b64 s[38:39], -1
	s_cbranch_scc1 .LBB0_312
	v_readlane_b32 s4, v255, 27
	v_readlane_b32 s46, v252, 45
	s_cmp_lt_i32 s4, 16
	v_readlane_b32 s47, v252, 46
	s_cbranch_scc1 .LBB0_295
	v_readlane_b32 s4, v255, 27
	s_cmp_lg_u32 s4, 16
	s_cbranch_scc0 .LBB0_282
	v_mov_b32_e32 v1, v185
	s_mov_b32 s4, s2
	v_mov_b32_e32 v2, v185
	s_nop 0
	v_ashrrev_i32_e32 v2, 6, v2
	v_lshl_add_u32 v2, s4, 2, v2
	s_movk_i32 s4, 0x4200
	v_cmp_gt_i32_e32 vcc, s4, v2
	s_and_saveexec_b64 s[38:39], vcc
	s_cbranch_execz .LBB0_250
	v_lshlrev_b32_e32 v1, 2, v1
	v_cmp_lt_i32_e32 vcc, v206, v205
	v_and_b32_e32 v3, 0xfc, v1
	v_readlane_b32 s4, v252, 33
	v_cndmask_b32_e32 v1, v204, v206, vcc
	v_cmp_lt_i32_e32 vcc, v207, v205
	v_lshlrev_b32_e32 v182, 1, v3
	v_readlane_b32 s5, v252, 34
	v_cndmask_b32_e32 v6, v204, v207, vcc
	v_cmp_lt_i32_e32 vcc, v208, v205
	s_waitcnt vmcnt(7)
	v_lshlrev_b32_e32 v16, 2, v6
	v_lshl_add_u64 v[4:5], s[4:5], 0, v[182:183]
	v_cndmask_b32_e32 v6, v204, v208, vcc
	v_cmp_lt_i32_e32 vcc, v209, v205
	v_lshlrev_b32_e32 v17, 2, v6
	v_readlane_b32 s4, v252, 61
	v_cndmask_b32_e32 v6, v204, v209, vcc
	v_cmp_lt_i32_e32 vcc, v210, v205
	v_lshlrev_b32_e32 v18, 2, v6
	v_lshlrev_b32_e32 v12, 2, v3
	v_cndmask_b32_e32 v6, v204, v210, vcc
	v_cmp_lt_i32_e32 vcc, v211, v205
	v_lshlrev_b32_e32 v19, 2, v6
	v_mov_b32_e32 v13, v183
	v_cndmask_b32_e32 v6, v204, v211, vcc
	v_readlane_b32 s5, v252, 62
	s_waitcnt vmcnt(5)
	v_lshlrev_b32_e32 v20, 2, v6
	v_lshlrev_b32_e32 v1, 2, v1
	v_lshl_add_u64 v[6:7], s[4:5], 0, v[12:13]
	v_readlane_b32 s4, v252, 59
	v_readlane_b32 s5, v252, 60
	v_lshl_add_u64 v[10:11], s[0:1], 0, v[182:183]
	s_mov_b64 s[40:41], 0
	v_lshl_add_u64 v[8:9], s[4:5], 0, v[12:13]
	v_readlane_b32 s4, v255, 5
	v_readlane_b32 s6, v255, 7
	v_readlane_b32 s7, v255, 8
	v_readlane_b32 s5, v255, 6
	v_readlane_b32 s8, v255, 9
	v_lshl_add_u64 v[12:13], s[6:7], 0, v[12:13]
	v_readlane_b32 s9, v255, 10
	v_readlane_b32 s10, v255, 11
	v_readlane_b32 s11, v255, 12
	v_ashrrev_i32_e32 v140, 31, v2
	v_mov_b32_e32 v236, v2
	v_mov_b32_e32 v237, v140
	v_lshlrev_b64 v[142:143], 11, v[236:237]
	v_lshl_add_u64 v[144:145], v[4:5], 0, v[142:143]
	global_load_dwordx2 v[146:147], v[144:145], off
	global_load_dwordx2 v[148:149], v[144:145], off offset:512
	global_load_dwordx2 v[150:151], v[144:145], off offset:1024
	global_load_dwordx2 v[152:153], v[144:145], off offset:1536
	global_load_dwordx4 v[154:157], v[6:7], off
	v_mov_b32_e32 v238, v2
	v_mov_b32_e32 v239, v140
	v_lshlrev_b64 v[158:159], 12, v[238:239]
	v_lshl_add_u64 v[160:161], v[12:13], 0, v[158:159]
	global_load_dwordx4 v[162:165], v[160:161], off nt
	global_load_dwordx4 v[166:169], v[160:161], off offset:1024 nt
	global_load_dwordx4 v[170:173], v[6:7], off offset:1024
	global_load_dwordx4 v[174:177], v[6:7], off offset:2048
	global_load_dwordx4 v[178:181], v[160:161], off offset:2048 nt
	global_load_dwordx4 v[186:189], v[160:161], off offset:3072 nt
	global_load_dwordx4 v[190:193], v[6:7], off offset:3072
	global_load_dwordx4 v[194:197], v[8:9], off
	global_load_dwordx4 v[224:227], v[8:9], off offset:1024
	global_load_dwordx4 v[228:231], v[8:9], off offset:2048
	global_load_dwordx4 v[232:235], v[8:9], off offset:3072
	s_waitcnt vmcnt(0)
.LBB0_249:
	v_add_u32_e32 v65, s3, v2
	v_min_i32_e32 v65, s64, v65
	v_ashrrev_i32_e32 v64, 31, v65
	v_mov_b32_e32 v130, v65
	v_mov_b32_e32 v131, v64
	v_lshlrev_b64 v[66:67], 11, v[130:131]
	v_lshl_add_u64 v[68:69], v[4:5], 0, v[66:67]
	global_load_dwordx2 v[70:71], v[68:69], off
	global_load_dwordx2 v[72:73], v[68:69], off offset:512
	global_load_dwordx2 v[74:75], v[68:69], off offset:1024
	global_load_dwordx2 v[76:77], v[68:69], off offset:1536
	global_load_dwordx4 v[78:81], v[6:7], off
	v_mov_b32_e32 v132, v65
	v_mov_b32_e32 v133, v64
	v_lshlrev_b64 v[82:83], 12, v[132:133]
	v_lshl_add_u64 v[84:85], v[12:13], 0, v[82:83]
	global_load_dwordx4 v[86:89], v[84:85], off nt
	global_load_dwordx4 v[90:93], v[84:85], off offset:1024 nt
	global_load_dwordx4 v[94:97], v[6:7], off offset:1024
	global_load_dwordx4 v[98:101], v[6:7], off offset:2048
	global_load_dwordx4 v[102:105], v[84:85], off offset:2048 nt
	global_load_dwordx4 v[106:109], v[84:85], off offset:3072 nt
	global_load_dwordx4 v[110:113], v[6:7], off offset:3072
	global_load_dwordx4 v[114:117], v[8:9], off
	global_load_dwordx4 v[118:121], v[8:9], off offset:1024
	global_load_dwordx4 v[122:125], v[8:9], off offset:2048
	global_load_dwordx4 v[126:129], v[8:9], off offset:3072
	s_nop 0
	s_nop 0
	s_nop 0
	s_nop 0
	s_nop 0
	s_nop 0
	s_nop 0
	s_nop 0
	s_nop 0
	s_nop 0
	s_nop 0
	s_nop 0
	v_lshl_add_u64 v[14:15], v[10:11], 0, v[142:143]
	v_add_u32_e32 v2, s3, v2
	s_waitcnt vmcnt(24)
	v_and_b32_e32 v39, 0xffff0000, v146
	s_waitcnt vmcnt(24)
	v_and_b32_e32 v45, 0xffff0000, v148
	v_lshlrev_b32_e32 v38, 16, v146
	v_lshlrev_b32_e32 v44, 16, v148
	v_lshlrev_b32_e32 v46, 16, v149
	v_and_b32_e32 v47, 0xffff0000, v149
	s_waitcnt vmcnt(24)
	v_and_b32_e32 v49, 0xffff0000, v150
	s_waitcnt vmcnt(24)
; DI void st_bf4(u16* p, float a, float b, float c, float d) { *(uint2*)p = make_uint2(pk2(a, b), pk2(c, d)); }
; DI void resid_norm(const Params& p, int layer, const u16* __restrict__ y) {
;     ...
;       ss += yv[i].x * yv[i].x + yv[i].y * yv[i].y + yv[i].z * yv[i].z + yv[i].w * yv[i].w;
;     }
;     ss = wave_sum(ss);
;     const float rs = rsqrtf(ss * (1.f / 1024.f) + 1e-6f);
;     float ss2 = 0.f;
; #pragma unroll
;     for (int i = 0; i < 4; ++i) {
;       const float4 gg = *(const float4*)(gpost + lane * 4 + 256 * i);
;       xv[i].x += yv[i].x * rs * gg.x; xv[i].y += yv[i].y * rs * gg.y; xv[i].z += yv[i].z * rs * gg.z; xv[i].w += yv[i].w * rs * gg.w;
;       __builtin_nontemporal_store((f32x4){xv[i].x, xv[i].y, xv[i].z, xv[i].w}, (f32x4*)(p.out + (size_t)r * 1024 + lane * 4 + 256 * i));
;       ss2 += xv[i].x * xv[i].x + xv[i].y * xv[i].y + xv[i].z * xv[i].z + xv[i].w * xv[i].w;
;     }
;     if (layer < 3) {
;       ss2 = wave_sum(ss2);
;       const float rs2 = rsqrtf(ss2 * (1.f / 1024.f) + 1e-6f);
; #pragma unroll
;       for (int i = 0; i < 4; ++i) {
;         const float4 gg = *(const float4*)(gpre + lane * 4 + 256 * i);
;         st_bf4(h + (size_t)r * 1024 + lane * 4 + 256 * i, xv[i].x * rs2 * gg.x, xv[i].y * rs2 * gg.y, xv[i].z * rs2 * gg.z, xv[i].w * rs2 * gg.w);
;       }
;     }
	v_and_b32_e32 v53, 0xffff0000, v152
	v_mov_b32_e32 v32, v39
	v_mov_b32_e32 v33, v45
	v_lshlrev_b32_e32 v40, 16, v147
	v_and_b32_e32 v41, 0xffff0000, v147
	v_lshlrev_b32_e32 v48, 16, v150
	v_lshlrev_b32_e32 v52, 16, v152
	v_mov_b32_e32 v30, v38
	v_mov_b32_e32 v31, v44
	v_mov_b32_e32 v58, v49
	v_mov_b32_e32 v59, v53
	v_pk_mul_f32 v[32:33], v[32:33], v[32:33]
	v_lshlrev_b32_e32 v50, 16, v151
	v_and_b32_e32 v51, 0xffff0000, v151
	v_lshlrev_b32_e32 v54, 16, v153
	v_mov_b32_e32 v34, v40
	v_mov_b32_e32 v35, v46
	v_mov_b32_e32 v56, v48
	v_mov_b32_e32 v57, v52
	v_pk_mul_f32 v[58:59], v[58:59], v[58:59]
	v_pk_fma_f32 v[30:31], v[30:31], v[30:31], v[32:33]
	v_and_b32_e32 v55, 0xffff0000, v153
	v_mov_b32_e32 v36, v41
	v_mov_b32_e32 v37, v47
	v_mov_b32_e32 v60, v50
	v_mov_b32_e32 v61, v54
	v_pk_fma_f32 v[32:33], v[56:57], v[56:57], v[58:59]
	v_pk_fma_f32 v[30:31], v[34:35], v[34:35], v[30:31]
	v_mov_b32_e32 v62, v51
	v_mov_b32_e32 v63, v55
	v_pk_fma_f32 v[32:33], v[60:61], v[60:61], v[32:33]
	v_pk_fma_f32 v[30:31], v[36:37], v[36:37], v[30:31]
	v_pk_fma_f32 v[32:33], v[62:63], v[62:63], v[32:33]
	v_add_f32_e32 v3, v30, v31
	v_add_f32_e32 v3, v3, v32
	v_add_f32_e32 v3, v3, v33
	v_mov_b32_e32 v21, v3
	s_nop 1
	v_permlane32_swap_b32_e32 v3, v21
	s_nop 0
	s_waitcnt lgkmcnt(0)
	v_add_f32_e32 v3, v3, v21
	v_mov_b32_e32 v21, v3
	s_nop 1
	v_permlane16_swap_b32_e32 v3, v21
	s_waitcnt lgkmcnt(0)
	v_add_f32_e32 v3, v3, v21
	s_nop 1
	v_mov_b32_dpp v21, v3 row_ror:8 row_mask:0xf bank_mask:0xf
	s_waitcnt lgkmcnt(0)
	v_add_f32_e32 v3, v3, v21
	s_nop 1
	v_mov_b32_dpp v21, v3 row_ror:4 row_mask:0xf bank_mask:0xf
	s_waitcnt lgkmcnt(0)
	v_add_f32_e32 v3, v3, v21
	s_nop 1
	v_mov_b32_dpp v21, v3 quad_perm:[2,3,0,1] row_mask:0xf bank_mask:0xf
	s_waitcnt lgkmcnt(0)
	v_add_f32_e32 v3, v3, v21
	s_nop 1
	v_mov_b32_dpp v21, v3 quad_perm:[1,0,3,2] row_mask:0xf bank_mask:0xf
	s_waitcnt lgkmcnt(0)
	v_add_f32_e32 v3, v3, v21
	v_fmamk_f32 v3, v3, 0x3a800000, v184
	v_mul_f32_e32 v21, 0x4b800000, v3
	v_cmp_gt_f32_e32 vcc, s33, v3
	s_nop 1
	v_cndmask_b32_e32 v3, v3, v21, vcc
	v_rsq_f32_e32 v3, v3
	s_nop 0
	v_mul_f32_e32 v21, 0x45800000, v3
	v_cndmask_b32_e32 v56, v3, v21, vcc
	v_pk_mul_f32 v[34:35], v[56:57], v[38:39] op_sel_hi:[0,1]
	v_pk_mul_f32 v[36:37], v[56:57], v[40:41] op_sel_hi:[0,1]
	s_waitcnt vmcnt(24)
	v_pk_fma_f32 v[22:23], v[154:155], v[34:35], v[162:163]
	v_pk_fma_f32 v[24:25], v[156:157], v[36:37], v[164:165]
	global_store_dwordx4 v[160:161], v[22:25], off nt
	s_nop 0
	v_pk_mul_f32 v[34:35], v[56:57], v[44:45] op_sel_hi:[0,1]
	v_pk_mul_f32 v[36:37], v[56:57], v[46:47] op_sel_hi:[0,1]
	v_pk_mul_f32 v[44:45], v[56:57], v[48:49] op_sel_hi:[0,1]
	v_pk_mul_f32 v[46:47], v[56:57], v[50:51] op_sel_hi:[0,1]
	v_mov_b32_e32 v48, v25
	s_waitcnt vmcnt(25)
	v_pk_fma_f32 v[26:27], v[170:171], v[34:35], v[166:167]
	v_pk_fma_f32 v[28:29], v[172:173], v[36:37], v[168:169]
	global_store_dwordx4 v[160:161], v[26:29], off offset:1024 nt
	s_nop 0
	s_nop 0
	s_nop 0
	v_mov_b32_e32 v49, v29
	s_waitcnt vmcnt(26)
	v_pk_fma_f32 v[30:31], v[174:175], v[44:45], v[178:179]
	v_pk_fma_f32 v[32:33], v[46:47], v[176:177], v[180:181]
	global_store_dwordx4 v[160:161], v[30:33], off offset:2048 nt
	s_nop 0
	v_pk_mul_f32 v[44:45], v[56:57], v[52:53] op_sel_hi:[0,1]
	v_pk_mul_f32 v[46:47], v[56:57], v[54:55] op_sel_hi:[0,1]
	s_waitcnt vmcnt(27)
	v_pk_fma_f32 v[34:35], v[44:45], v[190:191], v[186:187]
	v_pk_fma_f32 v[36:37], v[46:47], v[192:193], v[188:189]
	global_store_dwordx4 v[160:161], v[34:37], off offset:3072 nt
	s_nop 0
	v_mov_b32_e32 v44, v23
	v_mov_b32_e32 v45, v27
	v_mov_b32_e32 v42, v22
	v_mov_b32_e32 v43, v26
	v_pk_mul_f32 v[44:45], v[44:45], v[44:45]
	v_mov_b32_e32 v46, v24
	v_mov_b32_e32 v47, v28
	v_pk_fma_f32 v[42:43], v[42:43], v[42:43], v[44:45]
	v_mov_b32_e32 v44, v31
	v_pk_fma_f32 v[42:43], v[46:47], v[46:47], v[42:43]
	v_mov_b32_e32 v45, v35
	v_pk_fma_f32 v[42:43], v[48:49], v[48:49], v[42:43]
	v_pk_mul_f32 v[44:45], v[44:45], v[44:45]
	v_add_f32_e32 v3, v42, v43
	v_mov_b32_e32 v42, v30
	v_mov_b32_e32 v43, v34
	v_mov_b32_e32 v46, v32
	v_mov_b32_e32 v47, v36
	v_pk_fma_f32 v[42:43], v[42:43], v[42:43], v[44:45]
	v_mov_b32_e32 v48, v33
	v_mov_b32_e32 v49, v37
	v_pk_fma_f32 v[42:43], v[46:47], v[46:47], v[42:43]
	s_nop 0
	v_pk_fma_f32 v[42:43], v[48:49], v[48:49], v[42:43]
	s_nop 0
	v_add_f32_e32 v3, v42, v3
	v_add_f32_e32 v3, v3, v43
	v_mov_b32_e32 v21, v3
	s_nop 1
	v_permlane32_swap_b32_e32 v3, v21
	s_waitcnt lgkmcnt(0)
	v_add_f32_e32 v3, v3, v21
	v_mov_b32_e32 v21, v3
	s_nop 1
	v_permlane16_swap_b32_e32 v3, v21
	s_waitcnt lgkmcnt(0)
	v_add_f32_e32 v3, v3, v21
	s_nop 1
	v_mov_b32_dpp v21, v3 row_ror:8 row_mask:0xf bank_mask:0xf
	s_waitcnt lgkmcnt(0)
	v_add_f32_e32 v3, v3, v21
	s_nop 1
	v_mov_b32_dpp v21, v3 row_ror:4 row_mask:0xf bank_mask:0xf
	s_waitcnt lgkmcnt(0)
	v_add_f32_e32 v3, v3, v21
	s_nop 1
	v_mov_b32_dpp v21, v3 quad_perm:[2,3,0,1] row_mask:0xf bank_mask:0xf
	s_waitcnt lgkmcnt(0)
	v_add_f32_e32 v3, v3, v21
	s_nop 1
	v_mov_b32_dpp v21, v3 quad_perm:[1,0,3,2] row_mask:0xf bank_mask:0xf
	s_waitcnt lgkmcnt(0)
	v_add_f32_e32 v3, v3, v21
	v_fmamk_f32 v3, v3, 0x3a800000, v184
	v_mul_f32_e32 v21, 0x4b800000, v3
	v_cmp_gt_f32_e32 vcc, s33, v3
	s_nop 1
	v_cndmask_b32_e32 v3, v3, v21, vcc
	v_rsq_f32_e32 v3, v3
	s_nop 0
	v_mul_f32_e32 v21, 0x45800000, v3
	v_cndmask_b32_e32 v42, v3, v21, vcc
	v_pk_mul_f32 v[22:23], v[22:23], v[42:43] op_sel_hi:[1,0]
	v_pk_mul_f32 v[24:25], v[24:25], v[42:43] op_sel_hi:[1,0]
	v_pk_mul_f32 v[26:27], v[26:27], v[42:43] op_sel_hi:[1,0]
	v_pk_mul_f32 v[28:29], v[28:29], v[42:43] op_sel_hi:[1,0]
	s_waitcnt vmcnt(27)
	v_pk_mul_f32 v[22:23], v[194:195], v[22:23]
	v_pk_mul_f32 v[24:25], v[196:197], v[24:25]
	v_cvt_pk_bf16_f32 v22, v22, v23
	v_cvt_pk_bf16_f32 v23, v24, v25
	global_store_dwordx2 v[14:15], v[22:23], off
	s_nop 0
	v_cmp_lt_i32_e32 vcc, s64, v2
	s_or_b64 s[40:41], vcc, s[40:41]
	s_waitcnt vmcnt(26)
	v_pk_mul_f32 v[22:23], v[224:225], v[26:27]
	v_pk_mul_f32 v[24:25], v[226:227], v[28:29]
	v_cvt_pk_bf16_f32 v22, v22, v23
	v_cvt_pk_bf16_f32 v23, v24, v25
	global_store_dwordx2 v[14:15], v[22:23], off offset:512
	s_nop 0
	v_pk_mul_f32 v[26:27], v[30:31], v[42:43] op_sel_hi:[1,0]
	v_pk_mul_f32 v[28:29], v[32:33], v[42:43] op_sel_hi:[1,0]
	s_waitcnt vmcnt(25)
	v_pk_mul_f32 v[22:23], v[26:27], v[228:229]
	v_pk_mul_f32 v[24:25], v[28:29], v[230:231]
	v_cvt_pk_bf16_f32 v22, v22, v23
	v_cvt_pk_bf16_f32 v23, v24, v25
	global_store_dwordx2 v[14:15], v[22:23], off offset:1024
	s_nop 0
	v_pk_mul_f32 v[26:27], v[34:35], v[42:43] op_sel_hi:[1,0]
	v_pk_mul_f32 v[28:29], v[36:37], v[42:43] op_sel_hi:[1,0]
	s_waitcnt vmcnt(24)
	v_pk_mul_f32 v[22:23], v[26:27], v[232:233]
	v_pk_mul_f32 v[24:25], v[28:29], v[234:235]
	v_cvt_pk_bf16_f32 v22, v22, v23
	v_cvt_pk_bf16_f32 v23, v24, v25
	global_store_dwordx2 v[14:15], v[22:23], off offset:1536
	v_mov_b32_e32 v38, v194
	v_mov_b32_e32 v39, v195
	v_mov_b32_e32 v40, v196
	v_mov_b32_e32 v41, v197
	s_andn2_b64 exec, exec, s[40:41]
	s_cbranch_execz .Lrnp_exit_0
; DI int get_tid() { int t = threadIdx.x; asm volatile("" : "+v"(t)); return t; }
; DI int get_bid() { int b = blockIdx.x; asm volatile("" : "+s"(b)); return b; }
; DI float bflo(unsigned u) { return __uint_as_float(u << 16); }
; DI float bfhi(unsigned u) { return __uint_as_float(u & 0xffff0000u); }
; DI void resid_norm(const Params& p, int layer, const u16* __restrict__ y) {
;     ...
;   for (int r = get_bid() * 4 + (get_tid() >> 6); r < M_TOK; r += gridDim.x * 4) {
;     const float* x;
;     if (layer == 0) x = r < M_PROMPT ? p.x_prompt + (size_t)r * 1024 : p.x_sample + (size_t)(r - M_PROMPT) * 1024;
;     else x = p.out + (size_t)r * 1024;
;     float4 yv[4], xv[4]; float ss = 0.f;
; #pragma unroll
;     for (int i = 0; i < 4; ++i) {
;       { const uint2 yq = *(const uint2*)(y + (size_t)r * 1024 + lane * 4 + 256 * i); yv[i] = make_float4(bflo(yq.x), bfhi(yq.x), bflo(yq.y), bfhi(yq.y)); }
;       { const f32x4 t4 = __builtin_nontemporal_load((const f32x4*)(x + lane * 4 + 256 * i)); xv[i] = make_float4(t4[0], t4[1], t4[2], t4[3]); }
;       ss += yv[i].x * yv[i].x + yv[i].y * yv[i].y + yv[i].z * yv[i].z + yv[i].w * yv[i].w;
;     }
;     ss = wave_sum(ss);
;     const float rs = rsqrtf(ss * (1.f / 1024.f) + 1e-6f);
;     float ss2 = 0.f;
; #pragma unroll
;     for (int i = 0; i < 4; ++i) {
;       const float4 gg = *(const float4*)(gpost + lane * 4 + 256 * i);
;       xv[i].x += yv[i].x * rs * gg.x; xv[i].y += yv[i].y * rs * gg.y; xv[i].z += yv[i].z * rs * gg.z; xv[i].w += yv[i].w * rs * gg.w;
	v_add_u32_e32 v65, s3, v2
	v_min_i32_e32 v65, s64, v65
	v_ashrrev_i32_e32 v140, 31, v65
	v_mov_b32_e32 v236, v65
	v_mov_b32_e32 v237, v140
	v_lshlrev_b64 v[142:143], 11, v[236:237]
	v_lshl_add_u64 v[144:145], v[4:5], 0, v[142:143]
	global_load_dwordx2 v[146:147], v[144:145], off
	global_load_dwordx2 v[148:149], v[144:145], off offset:512
	global_load_dwordx2 v[150:151], v[144:145], off offset:1024
	global_load_dwordx2 v[152:153], v[144:145], off offset:1536
	global_load_dwordx4 v[154:157], v[6:7], off
	v_mov_b32_e32 v238, v65
	v_mov_b32_e32 v239, v140
	v_lshlrev_b64 v[158:159], 12, v[238:239]
	v_lshl_add_u64 v[160:161], v[12:13], 0, v[158:159]
	global_load_dwordx4 v[162:165], v[160:161], off nt
	global_load_dwordx4 v[166:169], v[160:161], off offset:1024 nt
	global_load_dwordx4 v[170:173], v[6:7], off offset:1024
	global_load_dwordx4 v[174:177], v[6:7], off offset:2048
	global_load_dwordx4 v[178:181], v[160:161], off offset:2048 nt
	global_load_dwordx4 v[186:189], v[160:161], off offset:3072 nt
	global_load_dwordx4 v[190:193], v[6:7], off offset:3072
	global_load_dwordx4 v[194:197], v[8:9], off
	global_load_dwordx4 v[224:227], v[8:9], off offset:1024
	global_load_dwordx4 v[228:231], v[8:9], off offset:2048
	global_load_dwordx4 v[232:235], v[8:9], off offset:3072
	s_nop 0
	s_nop 0
	s_nop 0
	s_nop 0
	s_nop 0
	s_nop 0
	s_nop 0
	s_nop 0
	s_nop 0
	s_nop 0
	s_nop 0
	s_nop 0
	v_lshl_add_u64 v[14:15], v[10:11], 0, v[66:67]
	v_add_u32_e32 v2, s3, v2
	s_waitcnt vmcnt(24)
	v_and_b32_e32 v39, 0xffff0000, v70
	s_waitcnt vmcnt(24)
	v_and_b32_e32 v45, 0xffff0000, v72
	v_lshlrev_b32_e32 v38, 16, v70
	v_lshlrev_b32_e32 v44, 16, v72
	v_lshlrev_b32_e32 v46, 16, v73
	v_and_b32_e32 v47, 0xffff0000, v73
	s_waitcnt vmcnt(24)
	v_and_b32_e32 v49, 0xffff0000, v74
	s_waitcnt vmcnt(24)
	v_and_b32_e32 v53, 0xffff0000, v76
	v_mov_b32_e32 v32, v39
	v_mov_b32_e32 v33, v45
	v_lshlrev_b32_e32 v40, 16, v71
	v_and_b32_e32 v41, 0xffff0000, v71
	v_lshlrev_b32_e32 v48, 16, v74
	v_lshlrev_b32_e32 v52, 16, v76
	v_mov_b32_e32 v30, v38
	v_mov_b32_e32 v31, v44
	v_mov_b32_e32 v58, v49
	v_mov_b32_e32 v59, v53
	v_pk_mul_f32 v[32:33], v[32:33], v[32:33]
	v_lshlrev_b32_e32 v50, 16, v75
	v_and_b32_e32 v51, 0xffff0000, v75
	v_lshlrev_b32_e32 v54, 16, v77
	v_mov_b32_e32 v34, v40
	v_mov_b32_e32 v35, v46
	v_mov_b32_e32 v56, v48
	v_mov_b32_e32 v57, v52
	v_pk_mul_f32 v[58:59], v[58:59], v[58:59]
	v_pk_fma_f32 v[30:31], v[30:31], v[30:31], v[32:33]
	v_and_b32_e32 v55, 0xffff0000, v77
	v_mov_b32_e32 v36, v41
	v_mov_b32_e32 v37, v47
	v_mov_b32_e32 v60, v50
	v_mov_b32_e32 v61, v54
	v_pk_fma_f32 v[32:33], v[56:57], v[56:57], v[58:59]
	v_pk_fma_f32 v[30:31], v[34:35], v[34:35], v[30:31]
	v_mov_b32_e32 v62, v51
	v_mov_b32_e32 v63, v55
	v_pk_fma_f32 v[32:33], v[60:61], v[60:61], v[32:33]
	v_pk_fma_f32 v[30:31], v[36:37], v[36:37], v[30:31]
	v_pk_fma_f32 v[32:33], v[62:63], v[62:63], v[32:33]
	v_add_f32_e32 v3, v30, v31
	v_add_f32_e32 v3, v3, v32
	v_add_f32_e32 v3, v3, v33
	v_mov_b32_e32 v21, v3
	s_nop 1
	v_permlane32_swap_b32_e32 v3, v21
	s_nop 0
	s_waitcnt lgkmcnt(0)
	v_add_f32_e32 v3, v3, v21
	v_mov_b32_e32 v21, v3
	s_nop 1
	v_permlane16_swap_b32_e32 v3, v21
	s_waitcnt lgkmcnt(0)
	v_add_f32_e32 v3, v3, v21
	s_nop 1
	v_mov_b32_dpp v21, v3 row_ror:8 row_mask:0xf bank_mask:0xf
	s_waitcnt lgkmcnt(0)
	v_add_f32_e32 v3, v3, v21
	s_nop 1
	v_mov_b32_dpp v21, v3 row_ror:4 row_mask:0xf bank_mask:0xf
	s_waitcnt lgkmcnt(0)
	v_add_f32_e32 v3, v3, v21
	s_nop 1
	v_mov_b32_dpp v21, v3 quad_perm:[2,3,0,1] row_mask:0xf bank_mask:0xf
	s_waitcnt lgkmcnt(0)
	v_add_f32_e32 v3, v3, v21
	s_nop 1
	v_mov_b32_dpp v21, v3 quad_perm:[1,0,3,2] row_mask:0xf bank_mask:0xf
	s_waitcnt lgkmcnt(0)
	v_add_f32_e32 v3, v3, v21
	v_fmamk_f32 v3, v3, 0x3a800000, v184
	v_mul_f32_e32 v21, 0x4b800000, v3
	v_cmp_gt_f32_e32 vcc, s33, v3
	s_nop 1
	v_cndmask_b32_e32 v3, v3, v21, vcc
	v_rsq_f32_e32 v3, v3
	s_nop 0
	v_mul_f32_e32 v21, 0x45800000, v3
	v_cndmask_b32_e32 v56, v3, v21, vcc
	v_pk_mul_f32 v[34:35], v[56:57], v[38:39] op_sel_hi:[0,1]
	v_pk_mul_f32 v[36:37], v[56:57], v[40:41] op_sel_hi:[0,1]
	s_waitcnt vmcnt(24)
	v_pk_fma_f32 v[22:23], v[78:79], v[34:35], v[86:87]
	v_pk_fma_f32 v[24:25], v[80:81], v[36:37], v[88:89]
	global_store_dwordx4 v[84:85], v[22:25], off nt
	s_nop 0
	v_pk_mul_f32 v[34:35], v[56:57], v[44:45] op_sel_hi:[0,1]
	v_pk_mul_f32 v[36:37], v[56:57], v[46:47] op_sel_hi:[0,1]
	v_pk_mul_f32 v[44:45], v[56:57], v[48:49] op_sel_hi:[0,1]
	v_pk_mul_f32 v[46:47], v[56:57], v[50:51] op_sel_hi:[0,1]
	v_mov_b32_e32 v48, v25
	s_waitcnt vmcnt(25)
	v_pk_fma_f32 v[26:27], v[94:95], v[34:35], v[90:91]
	v_pk_fma_f32 v[28:29], v[96:97], v[36:37], v[92:93]
	global_store_dwordx4 v[84:85], v[26:29], off offset:1024 nt
	s_nop 0
	s_nop 0
	s_nop 0
	v_mov_b32_e32 v49, v29
	s_waitcnt vmcnt(26)
; DI void st_bf4(u16* p, float a, float b, float c, float d) { *(uint2*)p = make_uint2(pk2(a, b), pk2(c, d)); }
; DI void convert_weights(const Params& p, int layer, char* smem) {
;     ...
;       } else {
;         const int idx = (t - 976) * 256 + tid;
;         const int pos = idx >> 5, i = idx & 31;
;         const float freq = exp2f(-(float)i * (13.287712379549449f / 32.f));
; DI void resid_norm(const Params& p, int layer, const u16* __restrict__ y) {
;     ...
;       xv[i].x += yv[i].x * rs * gg.x; xv[i].y += yv[i].y * rs * gg.y; xv[i].z += yv[i].z * rs * gg.z; xv[i].w += yv[i].w * rs * gg.w;
;       __builtin_nontemporal_store((f32x4){xv[i].x, xv[i].y, xv[i].z, xv[i].w}, (f32x4*)(p.out + (size_t)r * 1024 + lane * 4 + 256 * i));
;       ss2 += xv[i].x * xv[i].x + xv[i].y * xv[i].y + xv[i].z * xv[i].z + xv[i].w * xv[i].w;
;     }
;     if (layer < 3) {
;       ss2 = wave_sum(ss2);
;       const float rs2 = rsqrtf(ss2 * (1.f / 1024.f) + 1e-6f);
; #pragma unroll
;       for (int i = 0; i < 4; ++i) {
;         const float4 gg = *(const float4*)(gpre + lane * 4 + 256 * i);
;         st_bf4(h + (size_t)r * 1024 + lane * 4 + 256 * i, xv[i].x * rs2 * gg.x, xv[i].y * rs2 * gg.y, xv[i].z * rs2 * gg.z, xv[i].w * rs2 * gg.w);
;       }
;     }
	v_pk_fma_f32 v[30:31], v[98:99], v[44:45], v[102:103]
	v_pk_fma_f32 v[32:33], v[46:47], v[100:101], v[104:105]
	global_store_dwordx4 v[84:85], v[30:33], off offset:2048 nt
	s_nop 0
	v_pk_mul_f32 v[44:45], v[56:57], v[52:53] op_sel_hi:[0,1]
	v_pk_mul_f32 v[46:47], v[56:57], v[54:55] op_sel_hi:[0,1]
	s_waitcnt vmcnt(27)
	v_pk_fma_f32 v[34:35], v[44:45], v[110:111], v[106:107]
	v_pk_fma_f32 v[36:37], v[46:47], v[112:113], v[108:109]
	global_store_dwordx4 v[84:85], v[34:37], off offset:3072 nt
	s_nop 0
	v_mov_b32_e32 v44, v23
	v_mov_b32_e32 v45, v27
	v_mov_b32_e32 v42, v22
	v_mov_b32_e32 v43, v26
	v_pk_mul_f32 v[44:45], v[44:45], v[44:45]
	v_mov_b32_e32 v46, v24
	v_mov_b32_e32 v47, v28
	v_pk_fma_f32 v[42:43], v[42:43], v[42:43], v[44:45]
	v_mov_b32_e32 v44, v31
	v_pk_fma_f32 v[42:43], v[46:47], v[46:47], v[42:43]
	v_mov_b32_e32 v45, v35
	v_pk_fma_f32 v[42:43], v[48:49], v[48:49], v[42:43]
	v_pk_mul_f32 v[44:45], v[44:45], v[44:45]
	v_add_f32_e32 v3, v42, v43
	v_mov_b32_e32 v42, v30
	v_mov_b32_e32 v43, v34
	v_mov_b32_e32 v46, v32
	v_mov_b32_e32 v47, v36
	v_pk_fma_f32 v[42:43], v[42:43], v[42:43], v[44:45]
	v_mov_b32_e32 v48, v33
	v_mov_b32_e32 v49, v37
	v_pk_fma_f32 v[42:43], v[46:47], v[46:47], v[42:43]
	s_nop 0
	v_pk_fma_f32 v[42:43], v[48:49], v[48:49], v[42:43]
	s_nop 0
	v_add_f32_e32 v3, v42, v3
	v_add_f32_e32 v3, v3, v43
	v_mov_b32_e32 v21, v3
	s_nop 1
	v_permlane32_swap_b32_e32 v3, v21
	s_waitcnt lgkmcnt(0)
	v_add_f32_e32 v3, v3, v21
	v_mov_b32_e32 v21, v3
	s_nop 1
	v_permlane16_swap_b32_e32 v3, v21
	s_waitcnt lgkmcnt(0)
	v_add_f32_e32 v3, v3, v21
	s_nop 1
	v_mov_b32_dpp v21, v3 row_ror:8 row_mask:0xf bank_mask:0xf
	s_waitcnt lgkmcnt(0)
	v_add_f32_e32 v3, v3, v21
	s_nop 1
	v_mov_b32_dpp v21, v3 row_ror:4 row_mask:0xf bank_mask:0xf
	s_waitcnt lgkmcnt(0)
	v_add_f32_e32 v3, v3, v21
	s_nop 1
	v_mov_b32_dpp v21, v3 quad_perm:[2,3,0,1] row_mask:0xf bank_mask:0xf
	s_waitcnt lgkmcnt(0)
	v_add_f32_e32 v3, v3, v21
	s_nop 1
	v_mov_b32_dpp v21, v3 quad_perm:[1,0,3,2] row_mask:0xf bank_mask:0xf
	s_waitcnt lgkmcnt(0)
	v_add_f32_e32 v3, v3, v21
	v_fmamk_f32 v3, v3, 0x3a800000, v184
	v_mul_f32_e32 v21, 0x4b800000, v3
	v_cmp_gt_f32_e32 vcc, s33, v3
	s_nop 1
	v_cndmask_b32_e32 v3, v3, v21, vcc
	v_rsq_f32_e32 v3, v3
	s_nop 0
	v_mul_f32_e32 v21, 0x45800000, v3
	v_cndmask_b32_e32 v42, v3, v21, vcc
	v_pk_mul_f32 v[22:23], v[22:23], v[42:43] op_sel_hi:[1,0]
	v_pk_mul_f32 v[24:25], v[24:25], v[42:43] op_sel_hi:[1,0]
	v_pk_mul_f32 v[26:27], v[26:27], v[42:43] op_sel_hi:[1,0]
	v_pk_mul_f32 v[28:29], v[28:29], v[42:43] op_sel_hi:[1,0]
	s_waitcnt vmcnt(27)
	v_pk_mul_f32 v[22:23], v[114:115], v[22:23]
	v_pk_mul_f32 v[24:25], v[116:117], v[24:25]
	v_cvt_pk_bf16_f32 v22, v22, v23
	v_cvt_pk_bf16_f32 v23, v24, v25
	global_store_dwordx2 v[14:15], v[22:23], off
	s_nop 0
	v_cmp_lt_i32_e32 vcc, s64, v2
	s_or_b64 s[40:41], vcc, s[40:41]
	s_waitcnt vmcnt(26)
	v_pk_mul_f32 v[22:23], v[118:119], v[26:27]
	v_pk_mul_f32 v[24:25], v[120:121], v[28:29]
	v_cvt_pk_bf16_f32 v22, v22, v23
	v_cvt_pk_bf16_f32 v23, v24, v25
	global_store_dwordx2 v[14:15], v[22:23], off offset:512
	s_nop 0
	v_pk_mul_f32 v[26:27], v[30:31], v[42:43] op_sel_hi:[1,0]
	v_pk_mul_f32 v[28:29], v[32:33], v[42:43] op_sel_hi:[1,0]
	s_waitcnt vmcnt(25)
	v_pk_mul_f32 v[22:23], v[26:27], v[122:123]
	v_pk_mul_f32 v[24:25], v[28:29], v[124:125]
	v_cvt_pk_bf16_f32 v22, v22, v23
	v_cvt_pk_bf16_f32 v23, v24, v25
	global_store_dwordx2 v[14:15], v[22:23], off offset:1024
	s_nop 0
	v_pk_mul_f32 v[26:27], v[34:35], v[42:43] op_sel_hi:[1,0]
	v_pk_mul_f32 v[28:29], v[36:37], v[42:43] op_sel_hi:[1,0]
	s_waitcnt vmcnt(24)
	v_pk_mul_f32 v[22:23], v[26:27], v[126:127]
	v_pk_mul_f32 v[24:25], v[28:29], v[128:129]
	v_cvt_pk_bf16_f32 v22, v22, v23
	v_cvt_pk_bf16_f32 v23, v24, v25
	global_store_dwordx2 v[14:15], v[22:23], off offset:1536
	v_mov_b32_e32 v38, v114
	v_mov_b32_e32 v39, v115
	v_mov_b32_e32 v40, v116
	v_mov_b32_e32 v41, v117
	s_andn2_b64 exec, exec, s[40:41]
	s_cbranch_execnz .LBB0_249
.Lrnp_exit_0:
	s_waitcnt vmcnt(0)
.LBB0_250:
	s_or_b64 exec, exec, s[38:39]
	v_mov_b32_e32 v2, v185
	s_mov_b32 s4, s2
	s_cmpk_gt_i32 s4, 0x7cf
	s_cbranch_scc1 .LBB0_281
	v_and_b32_e32 v1, 31, v2
	v_cvt_f32_ubyte0_e32 v1, v1
	v_mul_f32_e32 v3, 0xbed49a78, v1
	s_mov_b32 s5, 0xc2fc0000
	v_cmp_gt_f32_e32 vcc, s5, v3
	v_readlane_b32 s8, v255, 5
	v_readlane_b32 s9, v255, 6
	v_cndmask_b32_e32 v3, 0, v215, vcc
	v_fmac_f32_e32 v3, 0xbed49a78, v1
	v_exp_f32_e32 v1, v3
	v_readlane_b32 s11, v255, 8
	v_cndmask_b32_e32 v3, 0, v216, vcc
	v_readlane_b32 s10, v255, 7
	v_readlane_b32 s12, v255, 9
	v_readlane_b32 s14, v255, 11
	v_lshl_add_u32 v2, s4, 8, v2
	s_lshl_b32 s8, s4, 2
	s_lshl_b32 s9, s4, 1
	s_lshl_b32 s11, s4, 5
	s_lshl_b32 s5, s4, 6
	v_ldexp_f32 v1, v1, v3
	s_lshl_b32 s6, s14, 6
	v_add_u32_e32 v8, 0xfffc3000, v2
	s_lshl_b32 s7, s14, 8
	s_add_i32 s8, s8, 0x7ffff4c0
	s_addk_i32 s9, 0xfb60
	s_lshl_b32 s10, s14, 1
	s_addk_i32 s11, 0xb600
	s_lshl_b32 s12, s14, 5
	v_readlane_b32 s13, v255, 10
	v_readlane_b32 s15, v255, 12
	s_branch .LBB0_254

; DI int get_tid() { int t = threadIdx.x; asm volatile("" : "+v"(t)); return t; }
; DI int get_bid() { int b = blockIdx.x; asm volatile("" : "+s"(b)); return b; }
; DI float bflo(unsigned u) { return __uint_as_float(u << 16); }
; DI float bfhi(unsigned u) { return __uint_as_float(u & 0xffff0000u); }
; DI void resid_norm(const Params& p, int layer, const u16* __restrict__ y) {
;     ...
;   for (int r = get_bid() * 4 + (get_tid() >> 6); r < M_TOK; r += gridDim.x * 4) {
;     const float* x;
;     if (layer == 0) x = r < M_PROMPT ? p.x_prompt + (size_t)r * 1024 : p.x_sample + (size_t)(r - M_PROMPT) * 1024;
;     else x = p.out + (size_t)r * 1024;
;     float4 yv[4], xv[4]; float ss = 0.f;
; #pragma unroll
;     for (int i = 0; i < 4; ++i) {
;       { const uint2 yq = *(const uint2*)(y + (size_t)r * 1024 + lane * 4 + 256 * i); yv[i] = make_float4(bflo(yq.x), bfhi(yq.x), bflo(yq.y), bfhi(yq.y)); }
;       { const f32x4 t4 = __builtin_nontemporal_load((const f32x4*)(x + lane * 4 + 256 * i)); xv[i] = make_float4(t4[0], t4[1], t4[2], t4[3]); }
;       ss += yv[i].x * yv[i].x + yv[i].y * yv[i].y + yv[i].z * yv[i].z + yv[i].w * yv[i].w;
; DI void run_phase(const Params& p, int ph, char* smem) {
;   if (ph == 0) { convert_weights(p, 0, smem); prenorm0(p); }
;   else if (ph <= 5) phase_even(p, 0, ph - 1, smem);
;   else if (ph <= 12) phase_odd(p, 0, ph - 6, smem);
.LBB0_873:
	s_and_b64 vcc, exec, s[38:39]
	s_cbranch_vccz .LBB0_883
	v_readlane_b32 s4, v255, 27
	s_cmp_lt_i32 s4, 9
	s_cbranch_scc1 .LBB0_897
	s_cmp_gt_i32 s4, 9
	s_mov_b64 s[38:39], -1
	s_cbranch_scc0 .LBB0_898
	s_cmp_gt_i32 s4, 10
	s_cbranch_scc0 .LBB0_913
	v_readlane_b32 s4, v255, 27
	s_cmp_lg_u32 s4, 11
	s_cbranch_scc0 .LBB0_900
	v_mov_b32_e32 v1, v185
	s_mov_b32 s4, s2
	v_mov_b32_e32 v0, v185
	s_nop 0
	v_ashrrev_i32_e32 v0, 6, v0
	v_lshl_add_u32 v0, s4, 2, v0
	s_movk_i32 s4, 0x4200
	v_cmp_gt_i32_e32 vcc, s4, v0
	s_and_saveexec_b64 s[38:39], vcc
	s_cbranch_execz .LBB0_881
	v_cmp_lt_i32_e32 vcc, v206, v205
	v_lshlrev_b32_e32 v1, 2, v1
	v_and_b32_e32 v1, 0xfc, v1
	v_cndmask_b32_e32 v4, v204, v206, vcc
	v_cmp_lt_i32_e32 vcc, v207, v205
	v_lshlrev_b32_e32 v14, 2, v4
	v_readlane_b32 s4, v253, 9
	v_cndmask_b32_e32 v4, v204, v207, vcc
	v_cmp_lt_i32_e32 vcc, v208, v205
	v_lshlrev_b32_e32 v15, 2, v4
	v_lshlrev_b32_e32 v10, 2, v1
	v_cndmask_b32_e32 v4, v204, v208, vcc
	v_cmp_lt_i32_e32 vcc, v209, v205
	s_waitcnt vmcnt(7)
	v_lshlrev_b32_e32 v16, 2, v4
	v_mov_b32_e32 v11, v183
	v_cndmask_b32_e32 v4, v204, v209, vcc
	v_cmp_lt_i32_e32 vcc, v210, v205
	v_lshlrev_b32_e32 v17, 2, v4
	v_readlane_b32 s5, v253, 10
	v_cndmask_b32_e32 v4, v204, v210, vcc
	v_cmp_lt_i32_e32 vcc, v211, v205
	s_waitcnt vmcnt(7)
	v_lshlrev_b32_e32 v18, 2, v4
	v_lshlrev_b32_e32 v182, 1, v1
	v_cndmask_b32_e32 v4, v204, v211, vcc
	v_lshlrev_b32_e32 v19, 2, v4
	v_lshl_add_u64 v[4:5], s[4:5], 0, v[10:11]
	v_readlane_b32 s4, v253, 7
	v_readlane_b32 s5, v253, 8
	v_lshl_add_u64 v[2:3], s[92:93], 0, v[182:183]
	v_lshl_add_u64 v[8:9], s[0:1], 0, v[182:183]
	v_lshl_add_u64 v[6:7], s[4:5], 0, v[10:11]
	v_readlane_b32 s4, v255, 5
	v_readlane_b32 s6, v255, 7
	v_readlane_b32 s7, v255, 8
	s_mov_b64 s[40:41], 0
	v_readlane_b32 s5, v255, 6
	v_lshl_add_u64 v[10:11], s[6:7], 0, v[10:11]
	v_readlane_b32 s8, v255, 9
	v_readlane_b32 s9, v255, 10
	v_readlane_b32 s10, v255, 11
	v_readlane_b32 s11, v255, 12
	v_ashrrev_i32_e32 v140, 31, v0
	v_mov_b32_e32 v236, v0
	v_mov_b32_e32 v237, v140
	v_lshlrev_b64 v[142:143], 11, v[236:237]
	v_lshl_add_u64 v[144:145], v[2:3], 0, v[142:143]
	global_load_dwordx2 v[146:147], v[144:145], off
	global_load_dwordx2 v[148:149], v[144:145], off offset:512
	global_load_dwordx2 v[150:151], v[144:145], off offset:1024
	global_load_dwordx2 v[152:153], v[144:145], off offset:1536
	global_load_dwordx4 v[154:157], v[4:5], off
	v_mov_b32_e32 v238, v0
	v_mov_b32_e32 v239, v140
	v_lshlrev_b64 v[158:159], 12, v[238:239]
	v_lshl_add_u64 v[160:161], v[10:11], 0, v[158:159]
	global_load_dwordx4 v[162:165], v[160:161], off nt
	global_load_dwordx4 v[166:169], v[160:161], off offset:1024 nt
	global_load_dwordx4 v[170:173], v[4:5], off offset:1024
	global_load_dwordx4 v[174:177], v[4:5], off offset:2048
	global_load_dwordx4 v[178:181], v[160:161], off offset:2048 nt
	global_load_dwordx4 v[186:189], v[160:161], off offset:3072 nt
	global_load_dwordx4 v[190:193], v[4:5], off offset:3072
	global_load_dwordx4 v[194:197], v[6:7], off
	global_load_dwordx4 v[224:227], v[6:7], off offset:1024
	global_load_dwordx4 v[228:231], v[6:7], off offset:2048
	global_load_dwordx4 v[232:235], v[6:7], off offset:3072
	s_waitcnt vmcnt(0)
.LBB0_880:
	v_add_u32_e32 v65, s3, v0
	v_min_i32_e32 v65, s64, v65
	v_ashrrev_i32_e32 v64, 31, v65
	v_mov_b32_e32 v130, v65
	v_mov_b32_e32 v131, v64
	v_lshlrev_b64 v[66:67], 11, v[130:131]
	v_lshl_add_u64 v[68:69], v[2:3], 0, v[66:67]
	global_load_dwordx2 v[70:71], v[68:69], off
	global_load_dwordx2 v[72:73], v[68:69], off offset:512
	global_load_dwordx2 v[74:75], v[68:69], off offset:1024
	global_load_dwordx2 v[76:77], v[68:69], off offset:1536
	global_load_dwordx4 v[78:81], v[4:5], off
	v_mov_b32_e32 v132, v65
	v_mov_b32_e32 v133, v64
	v_lshlrev_b64 v[82:83], 12, v[132:133]
	v_lshl_add_u64 v[84:85], v[10:11], 0, v[82:83]
	global_load_dwordx4 v[86:89], v[84:85], off nt
	global_load_dwordx4 v[90:93], v[84:85], off offset:1024 nt
	global_load_dwordx4 v[94:97], v[4:5], off offset:1024
	global_load_dwordx4 v[98:101], v[4:5], off offset:2048
	global_load_dwordx4 v[102:105], v[84:85], off offset:2048 nt
	global_load_dwordx4 v[106:109], v[84:85], off offset:3072 nt
	global_load_dwordx4 v[110:113], v[4:5], off offset:3072
	global_load_dwordx4 v[114:117], v[6:7], off
	global_load_dwordx4 v[118:121], v[6:7], off offset:1024
	global_load_dwordx4 v[122:125], v[6:7], off offset:2048
	global_load_dwordx4 v[126:129], v[6:7], off offset:3072
	s_nop 0
	s_nop 0
	s_waitcnt vmcnt(24)
	s_nop 0
	s_nop 0
	s_nop 0
	s_nop 0
	s_nop 0
	s_nop 0
	s_nop 0
	s_waitcnt vmcnt(24)
	s_nop 0
	s_nop 0
	s_nop 0
	v_lshl_add_u64 v[12:13], v[8:9], 0, v[142:143]
	v_add_u32_e32 v0, s3, v0
	s_waitcnt vmcnt(24)
	v_and_b32_e32 v37, 0xffff0000, v146
	s_waitcnt vmcnt(24)
	v_and_b32_e32 v43, 0xffff0000, v148
	v_lshlrev_b32_e32 v36, 16, v146
	v_lshlrev_b32_e32 v42, 16, v148
	v_lshlrev_b32_e32 v44, 16, v149
	v_and_b32_e32 v45, 0xffff0000, v149
	s_waitcnt vmcnt(24)
	v_and_b32_e32 v47, 0xffff0000, v150
	s_waitcnt vmcnt(24)
; DI int get_tid() { int t = threadIdx.x; asm volatile("" : "+v"(t)); return t; }
; DI int get_bid() { int b = blockIdx.x; asm volatile("" : "+s"(b)); return b; }
; DI float bflo(unsigned u) { return __uint_as_float(u << 16); }
; DI float bfhi(unsigned u) { return __uint_as_float(u & 0xffff0000u); }
; DI void st_bf4(u16* p, float a, float b, float c, float d) { *(uint2*)p = make_uint2(pk2(a, b), pk2(c, d)); }
; DI void resid_norm(const Params& p, int layer, const u16* __restrict__ y) {
;     ...
;   for (int r = get_bid() * 4 + (get_tid() >> 6); r < M_TOK; r += gridDim.x * 4) {
;     const float* x;
;     if (layer == 0) x = r < M_PROMPT ? p.x_prompt + (size_t)r * 1024 : p.x_sample + (size_t)(r - M_PROMPT) * 1024;
;     else x = p.out + (size_t)r * 1024;
;     float4 yv[4], xv[4]; float ss = 0.f;
; #pragma unroll
;     for (int i = 0; i < 4; ++i) {
;       { const uint2 yq = *(const uint2*)(y + (size_t)r * 1024 + lane * 4 + 256 * i); yv[i] = make_float4(bflo(yq.x), bfhi(yq.x), bflo(yq.y), bfhi(yq.y)); }
;       { const f32x4 t4 = __builtin_nontemporal_load((const f32x4*)(x + lane * 4 + 256 * i)); xv[i] = make_float4(t4[0], t4[1], t4[2], t4[3]); }
;       ss += yv[i].x * yv[i].x + yv[i].y * yv[i].y + yv[i].z * yv[i].z + yv[i].w * yv[i].w;
;     }
;     ss = wave_sum(ss);
;     const float rs = rsqrtf(ss * (1.f / 1024.f) + 1e-6f);
;     float ss2 = 0.f;
; #pragma unroll
;     for (int i = 0; i < 4; ++i) {
;       const float4 gg = *(const float4*)(gpost + lane * 4 + 256 * i);
;       xv[i].x += yv[i].x * rs * gg.x; xv[i].y += yv[i].y * rs * gg.y; xv[i].z += yv[i].z * rs * gg.z; xv[i].w += yv[i].w * rs * gg.w;
;       __builtin_nontemporal_store((f32x4){xv[i].x, xv[i].y, xv[i].z, xv[i].w}, (f32x4*)(p.out + (size_t)r * 1024 + lane * 4 + 256 * i));
;       ss2 += xv[i].x * xv[i].x + xv[i].y * xv[i].y + xv[i].z * xv[i].z + xv[i].w * xv[i].w;
;     }
;     if (layer < 3) {
;       ss2 = wave_sum(ss2);
;       const float rs2 = rsqrtf(ss2 * (1.f / 1024.f) + 1e-6f);
; #pragma unroll
;       for (int i = 0; i < 4; ++i) {
;         const float4 gg = *(const float4*)(gpre + lane * 4 + 256 * i);
;         st_bf4(h + (size_t)r * 1024 + lane * 4 + 256 * i, xv[i].x * rs2 * gg.x, xv[i].y * rs2 * gg.y, xv[i].z * rs2 * gg.z, xv[i].w * rs2 * gg.w);
;       }
	v_and_b32_e32 v51, 0xffff0000, v152
	v_mov_b32_e32 v30, v37
	v_mov_b32_e32 v31, v43
	v_lshlrev_b32_e32 v38, 16, v147
	v_and_b32_e32 v39, 0xffff0000, v147
	v_lshlrev_b32_e32 v46, 16, v150
	v_lshlrev_b32_e32 v50, 16, v152
	v_mov_b32_e32 v28, v36
	v_mov_b32_e32 v29, v42
	v_mov_b32_e32 v56, v47
	v_mov_b32_e32 v57, v51
	v_pk_mul_f32 v[30:31], v[30:31], v[30:31]
	v_lshlrev_b32_e32 v48, 16, v151
	v_and_b32_e32 v49, 0xffff0000, v151
	v_lshlrev_b32_e32 v52, 16, v153
	v_mov_b32_e32 v32, v38
	v_mov_b32_e32 v33, v44
	v_mov_b32_e32 v54, v46
	v_mov_b32_e32 v55, v50
	v_pk_mul_f32 v[56:57], v[56:57], v[56:57]
	v_pk_fma_f32 v[28:29], v[28:29], v[28:29], v[30:31]
	v_and_b32_e32 v53, 0xffff0000, v153
	v_mov_b32_e32 v34, v39
	v_mov_b32_e32 v35, v45
	v_mov_b32_e32 v58, v48
	v_mov_b32_e32 v59, v52
	v_pk_fma_f32 v[30:31], v[54:55], v[54:55], v[56:57]
	v_pk_fma_f32 v[28:29], v[32:33], v[32:33], v[28:29]
	v_mov_b32_e32 v60, v49
	v_mov_b32_e32 v61, v53
	v_pk_fma_f32 v[30:31], v[58:59], v[58:59], v[30:31]
	v_pk_fma_f32 v[28:29], v[34:35], v[34:35], v[28:29]
	v_pk_fma_f32 v[30:31], v[60:61], v[60:61], v[30:31]
	v_add_f32_e32 v1, v28, v29
	v_add_f32_e32 v1, v1, v30
	v_add_f32_e32 v1, v1, v31
	v_mov_b32_e32 v28, v1
	s_nop 1
	v_permlane32_swap_b32_e32 v1, v28
	s_waitcnt lgkmcnt(0)
	v_add_f32_e32 v1, v1, v28
	v_mov_b32_e32 v28, v1
	s_nop 1
	v_permlane16_swap_b32_e32 v1, v28
	s_waitcnt lgkmcnt(0)
	v_add_f32_e32 v1, v1, v28
	s_nop 1
	v_mov_b32_dpp v28, v1 row_ror:8 row_mask:0xf bank_mask:0xf
	s_waitcnt lgkmcnt(0)
	v_add_f32_e32 v1, v1, v28
	s_nop 1
	v_mov_b32_dpp v28, v1 row_ror:4 row_mask:0xf bank_mask:0xf
	s_waitcnt lgkmcnt(0)
	v_add_f32_e32 v1, v1, v28
	s_nop 1
	v_mov_b32_dpp v28, v1 quad_perm:[2,3,0,1] row_mask:0xf bank_mask:0xf
	s_waitcnt lgkmcnt(0)
	v_add_f32_e32 v1, v1, v28
	s_nop 1
	v_mov_b32_dpp v28, v1 quad_perm:[1,0,3,2] row_mask:0xf bank_mask:0xf
	s_waitcnt lgkmcnt(0)
	v_add_f32_e32 v1, v1, v28
	v_fmamk_f32 v1, v1, 0x3a800000, v184
	v_mul_f32_e32 v28, 0x4b800000, v1
	v_cmp_gt_f32_e32 vcc, s33, v1
	s_nop 1
	v_cndmask_b32_e32 v1, v1, v28, vcc
	v_rsq_f32_e32 v1, v1
	s_nop 0
	v_mul_f32_e32 v32, 0x45800000, v1
	v_cndmask_b32_e32 v54, v1, v32, vcc
	v_pk_mul_f32 v[32:33], v[54:55], v[36:37] op_sel_hi:[0,1]
	v_pk_mul_f32 v[34:35], v[54:55], v[38:39] op_sel_hi:[0,1]
	s_waitcnt vmcnt(24)
	v_pk_fma_f32 v[20:21], v[154:155], v[32:33], v[162:163]
	v_pk_fma_f32 v[22:23], v[156:157], v[34:35], v[164:165]
	global_store_dwordx4 v[160:161], v[20:23], off nt
	s_nop 0
	v_pk_mul_f32 v[32:33], v[54:55], v[42:43] op_sel_hi:[0,1]
	v_pk_mul_f32 v[34:35], v[54:55], v[44:45] op_sel_hi:[0,1]
	v_pk_mul_f32 v[42:43], v[54:55], v[46:47] op_sel_hi:[0,1]
	v_pk_mul_f32 v[44:45], v[54:55], v[48:49] op_sel_hi:[0,1]
	v_mov_b32_e32 v46, v23
	s_waitcnt vmcnt(25)
	v_pk_fma_f32 v[24:25], v[170:171], v[32:33], v[166:167]
	v_pk_fma_f32 v[26:27], v[172:173], v[34:35], v[168:169]
	global_store_dwordx4 v[160:161], v[24:27], off offset:1024 nt
	s_nop 0
	s_nop 0
	s_nop 0
	v_mov_b32_e32 v47, v27
	s_waitcnt vmcnt(26)
	v_pk_fma_f32 v[28:29], v[174:175], v[42:43], v[178:179]
	v_pk_fma_f32 v[30:31], v[44:45], v[176:177], v[180:181]
	global_store_dwordx4 v[160:161], v[28:31], off offset:2048 nt
	s_nop 0
	v_pk_mul_f32 v[42:43], v[54:55], v[50:51] op_sel_hi:[0,1]
	v_pk_mul_f32 v[44:45], v[54:55], v[52:53] op_sel_hi:[0,1]
	s_waitcnt vmcnt(27)
	v_pk_fma_f32 v[32:33], v[42:43], v[190:191], v[186:187]
	v_pk_fma_f32 v[34:35], v[44:45], v[192:193], v[188:189]
	global_store_dwordx4 v[160:161], v[32:35], off offset:3072 nt
	s_nop 0
	v_mov_b32_e32 v42, v21
	v_mov_b32_e32 v43, v25
	v_mov_b32_e32 v40, v20
	v_mov_b32_e32 v41, v24
	v_pk_mul_f32 v[42:43], v[42:43], v[42:43]
	v_mov_b32_e32 v44, v22
	v_mov_b32_e32 v45, v26
	v_pk_fma_f32 v[40:41], v[40:41], v[40:41], v[42:43]
	v_mov_b32_e32 v42, v29
	v_pk_fma_f32 v[40:41], v[44:45], v[44:45], v[40:41]
	v_mov_b32_e32 v43, v33
	v_pk_fma_f32 v[40:41], v[46:47], v[46:47], v[40:41]
	v_pk_mul_f32 v[42:43], v[42:43], v[42:43]
	v_add_f32_e32 v1, v40, v41
	v_mov_b32_e32 v40, v28
	v_mov_b32_e32 v41, v32
	v_mov_b32_e32 v44, v30
	v_mov_b32_e32 v45, v34
	v_pk_fma_f32 v[40:41], v[40:41], v[40:41], v[42:43]
	v_mov_b32_e32 v46, v31
	v_mov_b32_e32 v47, v35
	v_pk_fma_f32 v[40:41], v[44:45], v[44:45], v[40:41]
	s_nop 0
	v_pk_fma_f32 v[40:41], v[46:47], v[46:47], v[40:41]
	s_nop 0
	v_add_f32_e32 v1, v40, v1
	v_add_f32_e32 v1, v1, v41
	v_mov_b32_e32 v40, v1
	s_nop 1
	v_permlane32_swap_b32_e32 v1, v40
	s_waitcnt lgkmcnt(0)
	v_add_f32_e32 v1, v1, v40
	v_mov_b32_e32 v40, v1
	s_nop 1
	v_permlane16_swap_b32_e32 v1, v40
	s_waitcnt lgkmcnt(0)
	v_add_f32_e32 v1, v1, v40
	s_nop 1
	v_mov_b32_dpp v40, v1 row_ror:8 row_mask:0xf bank_mask:0xf
	s_waitcnt lgkmcnt(0)
	v_add_f32_e32 v1, v1, v40
	s_nop 1
	v_mov_b32_dpp v40, v1 row_ror:4 row_mask:0xf bank_mask:0xf
	s_waitcnt lgkmcnt(0)
	v_add_f32_e32 v1, v1, v40
	s_nop 1
	v_mov_b32_dpp v40, v1 quad_perm:[2,3,0,1] row_mask:0xf bank_mask:0xf
	s_waitcnt lgkmcnt(0)
	v_add_f32_e32 v1, v1, v40
	s_nop 1
	v_mov_b32_dpp v40, v1 quad_perm:[1,0,3,2] row_mask:0xf bank_mask:0xf
	s_waitcnt lgkmcnt(0)
	v_add_f32_e32 v1, v1, v40
	v_fmamk_f32 v1, v1, 0x3a800000, v184
	v_mul_f32_e32 v40, 0x4b800000, v1
	v_cmp_gt_f32_e32 vcc, s33, v1
	s_nop 1
	v_cndmask_b32_e32 v1, v1, v40, vcc
	v_rsq_f32_e32 v1, v1
	s_nop 0
	v_mul_f32_e32 v40, 0x45800000, v1
	v_cndmask_b32_e32 v40, v1, v40, vcc
	v_pk_mul_f32 v[20:21], v[20:21], v[40:41] op_sel_hi:[1,0]
	v_pk_mul_f32 v[22:23], v[22:23], v[40:41] op_sel_hi:[1,0]
	v_pk_mul_f32 v[24:25], v[24:25], v[40:41] op_sel_hi:[1,0]
	v_pk_mul_f32 v[26:27], v[26:27], v[40:41] op_sel_hi:[1,0]
	s_waitcnt vmcnt(27)
	v_pk_mul_f32 v[20:21], v[194:195], v[20:21]
	v_pk_mul_f32 v[22:23], v[196:197], v[22:23]
	v_cvt_pk_bf16_f32 v20, v20, v21
	v_cvt_pk_bf16_f32 v21, v22, v23
	global_store_dwordx2 v[12:13], v[20:21], off
	s_nop 0
	v_cmp_lt_i32_e32 vcc, s64, v0
	s_or_b64 s[40:41], vcc, s[40:41]
	s_waitcnt vmcnt(26)
	v_pk_mul_f32 v[20:21], v[224:225], v[24:25]
	v_pk_mul_f32 v[22:23], v[226:227], v[26:27]
	v_cvt_pk_bf16_f32 v20, v20, v21
	v_cvt_pk_bf16_f32 v21, v22, v23
	global_store_dwordx2 v[12:13], v[20:21], off offset:512
	s_nop 0
	v_pk_mul_f32 v[24:25], v[28:29], v[40:41] op_sel_hi:[1,0]
	v_pk_mul_f32 v[26:27], v[30:31], v[40:41] op_sel_hi:[1,0]
	s_waitcnt vmcnt(25)
	v_pk_mul_f32 v[20:21], v[24:25], v[228:229]
	v_pk_mul_f32 v[22:23], v[26:27], v[230:231]
	v_cvt_pk_bf16_f32 v20, v20, v21
	v_cvt_pk_bf16_f32 v21, v22, v23
	global_store_dwordx2 v[12:13], v[20:21], off offset:1024
	s_nop 0
	v_pk_mul_f32 v[24:25], v[32:33], v[40:41] op_sel_hi:[1,0]
	v_pk_mul_f32 v[26:27], v[34:35], v[40:41] op_sel_hi:[1,0]
	s_waitcnt vmcnt(24)
	v_pk_mul_f32 v[20:21], v[24:25], v[232:233]
	v_pk_mul_f32 v[22:23], v[26:27], v[234:235]
	v_cvt_pk_bf16_f32 v20, v20, v21
	v_cvt_pk_bf16_f32 v21, v22, v23
	global_store_dwordx2 v[12:13], v[20:21], off offset:1536
	v_mov_b32_e32 v36, v194
	v_mov_b32_e32 v37, v195
	v_mov_b32_e32 v38, v196
	v_mov_b32_e32 v39, v197
	s_andn2_b64 exec, exec, s[40:41]
	s_cbranch_execz .Lrnp_exit_1
; DI int get_tid() { int t = threadIdx.x; asm volatile("" : "+v"(t)); return t; }
; DI int get_bid() { int b = blockIdx.x; asm volatile("" : "+s"(b)); return b; }
; DI float bflo(unsigned u) { return __uint_as_float(u << 16); }
; DI float bfhi(unsigned u) { return __uint_as_float(u & 0xffff0000u); }
; DI void resid_norm(const Params& p, int layer, const u16* __restrict__ y) {
;     ...
;   for (int r = get_bid() * 4 + (get_tid() >> 6); r < M_TOK; r += gridDim.x * 4) {
;     const float* x;
;     if (layer == 0) x = r < M_PROMPT ? p.x_prompt + (size_t)r * 1024 : p.x_sample + (size_t)(r - M_PROMPT) * 1024;
;     else x = p.out + (size_t)r * 1024;
;     float4 yv[4], xv[4]; float ss = 0.f;
; #pragma unroll
;     for (int i = 0; i < 4; ++i) {
;       { const uint2 yq = *(const uint2*)(y + (size_t)r * 1024 + lane * 4 + 256 * i); yv[i] = make_float4(bflo(yq.x), bfhi(yq.x), bflo(yq.y), bfhi(yq.y)); }
;       { const f32x4 t4 = __builtin_nontemporal_load((const f32x4*)(x + lane * 4 + 256 * i)); xv[i] = make_float4(t4[0], t4[1], t4[2], t4[3]); }
;       ss += yv[i].x * yv[i].x + yv[i].y * yv[i].y + yv[i].z * yv[i].z + yv[i].w * yv[i].w;
;     }
;     ss = wave_sum(ss);
;     const float rs = rsqrtf(ss * (1.f / 1024.f) + 1e-6f);
;     float ss2 = 0.f;
; #pragma unroll
;     for (int i = 0; i < 4; ++i) {
;       const float4 gg = *(const float4*)(gpost + lane * 4 + 256 * i);
;       xv[i].x += yv[i].x * rs * gg.x; xv[i].y += yv[i].y * rs * gg.y; xv[i].z += yv[i].z * rs * gg.z; xv[i].w += yv[i].w * rs * gg.w;
;       __builtin_nontemporal_store((f32x4){xv[i].x, xv[i].y, xv[i].z, xv[i].w}, (f32x4*)(p.out + (size_t)r * 1024 + lane * 4 + 256 * i));
;       ss2 += xv[i].x * xv[i].x + xv[i].y * xv[i].y + xv[i].z * xv[i].z + xv[i].w * xv[i].w;
;     }
	v_add_u32_e32 v65, s3, v0
	v_min_i32_e32 v65, s64, v65
	v_ashrrev_i32_e32 v140, 31, v65
	v_mov_b32_e32 v236, v65
	v_mov_b32_e32 v237, v140
	v_lshlrev_b64 v[142:143], 11, v[236:237]
	v_lshl_add_u64 v[144:145], v[2:3], 0, v[142:143]
	global_load_dwordx2 v[146:147], v[144:145], off
	global_load_dwordx2 v[148:149], v[144:145], off offset:512
	global_load_dwordx2 v[150:151], v[144:145], off offset:1024
	global_load_dwordx2 v[152:153], v[144:145], off offset:1536
	global_load_dwordx4 v[154:157], v[4:5], off
	v_mov_b32_e32 v238, v65
	v_mov_b32_e32 v239, v140
	v_lshlrev_b64 v[158:159], 12, v[238:239]
	v_lshl_add_u64 v[160:161], v[10:11], 0, v[158:159]
	global_load_dwordx4 v[162:165], v[160:161], off nt
	global_load_dwordx4 v[166:169], v[160:161], off offset:1024 nt
	global_load_dwordx4 v[170:173], v[4:5], off offset:1024
	global_load_dwordx4 v[174:177], v[4:5], off offset:2048
	global_load_dwordx4 v[178:181], v[160:161], off offset:2048 nt
	global_load_dwordx4 v[186:189], v[160:161], off offset:3072 nt
	global_load_dwordx4 v[190:193], v[4:5], off offset:3072
	global_load_dwordx4 v[194:197], v[6:7], off
	global_load_dwordx4 v[224:227], v[6:7], off offset:1024
	global_load_dwordx4 v[228:231], v[6:7], off offset:2048
	global_load_dwordx4 v[232:235], v[6:7], off offset:3072
	s_nop 0
	s_nop 0
	s_waitcnt vmcnt(24)
	s_nop 0
	s_nop 0
	s_nop 0
	s_nop 0
	s_nop 0
	s_nop 0
	s_nop 0
	s_waitcnt vmcnt(24)
	s_nop 0
	s_nop 0
	s_nop 0
	v_lshl_add_u64 v[12:13], v[8:9], 0, v[66:67]
	v_add_u32_e32 v0, s3, v0
	s_waitcnt vmcnt(24)
	v_and_b32_e32 v37, 0xffff0000, v70
	s_waitcnt vmcnt(24)
	v_and_b32_e32 v43, 0xffff0000, v72
	v_lshlrev_b32_e32 v36, 16, v70
	v_lshlrev_b32_e32 v42, 16, v72
	v_lshlrev_b32_e32 v44, 16, v73
	v_and_b32_e32 v45, 0xffff0000, v73
	s_waitcnt vmcnt(24)
	v_and_b32_e32 v47, 0xffff0000, v74
	s_waitcnt vmcnt(24)
	v_and_b32_e32 v51, 0xffff0000, v76
	v_mov_b32_e32 v30, v37
	v_mov_b32_e32 v31, v43
	v_lshlrev_b32_e32 v38, 16, v71
	v_and_b32_e32 v39, 0xffff0000, v71
	v_lshlrev_b32_e32 v46, 16, v74
	v_lshlrev_b32_e32 v50, 16, v76
	v_mov_b32_e32 v28, v36
	v_mov_b32_e32 v29, v42
	v_mov_b32_e32 v56, v47
	v_mov_b32_e32 v57, v51
	v_pk_mul_f32 v[30:31], v[30:31], v[30:31]
	v_lshlrev_b32_e32 v48, 16, v75
	v_and_b32_e32 v49, 0xffff0000, v75
	v_lshlrev_b32_e32 v52, 16, v77
	v_mov_b32_e32 v32, v38
	v_mov_b32_e32 v33, v44
	v_mov_b32_e32 v54, v46
	v_mov_b32_e32 v55, v50
	v_pk_mul_f32 v[56:57], v[56:57], v[56:57]
	v_pk_fma_f32 v[28:29], v[28:29], v[28:29], v[30:31]
	v_and_b32_e32 v53, 0xffff0000, v77
	v_mov_b32_e32 v34, v39
	v_mov_b32_e32 v35, v45
	v_mov_b32_e32 v58, v48
	v_mov_b32_e32 v59, v52
	v_pk_fma_f32 v[30:31], v[54:55], v[54:55], v[56:57]
	v_pk_fma_f32 v[28:29], v[32:33], v[32:33], v[28:29]
	v_mov_b32_e32 v60, v49
	v_mov_b32_e32 v61, v53
	v_pk_fma_f32 v[30:31], v[58:59], v[58:59], v[30:31]
	v_pk_fma_f32 v[28:29], v[34:35], v[34:35], v[28:29]
	v_pk_fma_f32 v[30:31], v[60:61], v[60:61], v[30:31]
	v_add_f32_e32 v1, v28, v29
	v_add_f32_e32 v1, v1, v30
	v_add_f32_e32 v1, v1, v31
	v_mov_b32_e32 v28, v1
	s_nop 1
	v_permlane32_swap_b32_e32 v1, v28
	s_waitcnt lgkmcnt(0)
	v_add_f32_e32 v1, v1, v28
	v_mov_b32_e32 v28, v1
	s_nop 1
	v_permlane16_swap_b32_e32 v1, v28
	s_waitcnt lgkmcnt(0)
	v_add_f32_e32 v1, v1, v28
	s_nop 1
	v_mov_b32_dpp v28, v1 row_ror:8 row_mask:0xf bank_mask:0xf
	s_waitcnt lgkmcnt(0)
	v_add_f32_e32 v1, v1, v28
	s_nop 1
	v_mov_b32_dpp v28, v1 row_ror:4 row_mask:0xf bank_mask:0xf
	s_waitcnt lgkmcnt(0)
	v_add_f32_e32 v1, v1, v28
	s_nop 1
	v_mov_b32_dpp v28, v1 quad_perm:[2,3,0,1] row_mask:0xf bank_mask:0xf
	s_waitcnt lgkmcnt(0)
	v_add_f32_e32 v1, v1, v28
	s_nop 1
	v_mov_b32_dpp v28, v1 quad_perm:[1,0,3,2] row_mask:0xf bank_mask:0xf
	s_waitcnt lgkmcnt(0)
	v_add_f32_e32 v1, v1, v28
	v_fmamk_f32 v1, v1, 0x3a800000, v184
	v_mul_f32_e32 v28, 0x4b800000, v1
	v_cmp_gt_f32_e32 vcc, s33, v1
	s_nop 1
	v_cndmask_b32_e32 v1, v1, v28, vcc
	v_rsq_f32_e32 v1, v1
	s_nop 0
	v_mul_f32_e32 v32, 0x45800000, v1
	v_cndmask_b32_e32 v54, v1, v32, vcc
	v_pk_mul_f32 v[32:33], v[54:55], v[36:37] op_sel_hi:[0,1]
	v_pk_mul_f32 v[34:35], v[54:55], v[38:39] op_sel_hi:[0,1]
	s_waitcnt vmcnt(24)
	v_pk_fma_f32 v[20:21], v[78:79], v[32:33], v[86:87]
	v_pk_fma_f32 v[22:23], v[80:81], v[34:35], v[88:89]
	global_store_dwordx4 v[84:85], v[20:23], off nt
	s_nop 0
	v_pk_mul_f32 v[32:33], v[54:55], v[42:43] op_sel_hi:[0,1]
	v_pk_mul_f32 v[34:35], v[54:55], v[44:45] op_sel_hi:[0,1]
	v_pk_mul_f32 v[42:43], v[54:55], v[46:47] op_sel_hi:[0,1]
	v_pk_mul_f32 v[44:45], v[54:55], v[48:49] op_sel_hi:[0,1]
	v_mov_b32_e32 v46, v23
	s_waitcnt vmcnt(25)
	v_pk_fma_f32 v[24:25], v[94:95], v[32:33], v[90:91]
	v_pk_fma_f32 v[26:27], v[96:97], v[34:35], v[92:93]
	global_store_dwordx4 v[84:85], v[24:27], off offset:1024 nt
	s_nop 0
	s_nop 0
	s_nop 0
	v_mov_b32_e32 v47, v27
	s_waitcnt vmcnt(26)
; DI int get_bid() { int b = blockIdx.x; asm volatile("" : "+s"(b)); return b; }
; DI void st_bf4(u16* p, float a, float b, float c, float d) { *(uint2*)p = make_uint2(pk2(a, b), pk2(c, d)); }
; DI void convert_weights(const Params& p, int layer, char* smem) {
;     ...
;     for (int t = get_bid(); t < 1920; t += gridDim.x) {
;       if (t < 1280) {
;         tconv_tile(p.w_in_even + (size_t)e * 1024 * 5120, 5120, 5120, W + WE_IN, 1024, (t / 80) * 64, (t % 80) * 64, smem);
; DI void resid_norm(const Params& p, int layer, const u16* __restrict__ y) {
;     ...
;     for (int i = 0; i < 4; ++i) {
;       const float4 gg = *(const float4*)(gpost + lane * 4 + 256 * i);
;       xv[i].x += yv[i].x * rs * gg.x; xv[i].y += yv[i].y * rs * gg.y; xv[i].z += yv[i].z * rs * gg.z; xv[i].w += yv[i].w * rs * gg.w;
;       __builtin_nontemporal_store((f32x4){xv[i].x, xv[i].y, xv[i].z, xv[i].w}, (f32x4*)(p.out + (size_t)r * 1024 + lane * 4 + 256 * i));
;       ss2 += xv[i].x * xv[i].x + xv[i].y * xv[i].y + xv[i].z * xv[i].z + xv[i].w * xv[i].w;
;     }
;     if (layer < 3) {
;       ss2 = wave_sum(ss2);
;       const float rs2 = rsqrtf(ss2 * (1.f / 1024.f) + 1e-6f);
; #pragma unroll
;       for (int i = 0; i < 4; ++i) {
;         const float4 gg = *(const float4*)(gpre + lane * 4 + 256 * i);
;         st_bf4(h + (size_t)r * 1024 + lane * 4 + 256 * i, xv[i].x * rs2 * gg.x, xv[i].y * rs2 * gg.y, xv[i].z * rs2 * gg.z, xv[i].w * rs2 * gg.w);
;       }
	v_pk_fma_f32 v[28:29], v[98:99], v[42:43], v[102:103]
	v_pk_fma_f32 v[30:31], v[44:45], v[100:101], v[104:105]
	global_store_dwordx4 v[84:85], v[28:31], off offset:2048 nt
	s_nop 0
	v_pk_mul_f32 v[42:43], v[54:55], v[50:51] op_sel_hi:[0,1]
	v_pk_mul_f32 v[44:45], v[54:55], v[52:53] op_sel_hi:[0,1]
	s_waitcnt vmcnt(27)
	v_pk_fma_f32 v[32:33], v[42:43], v[110:111], v[106:107]
	v_pk_fma_f32 v[34:35], v[44:45], v[112:113], v[108:109]
	global_store_dwordx4 v[84:85], v[32:35], off offset:3072 nt
	s_nop 0
	v_mov_b32_e32 v42, v21
	v_mov_b32_e32 v43, v25
	v_mov_b32_e32 v40, v20
	v_mov_b32_e32 v41, v24
	v_pk_mul_f32 v[42:43], v[42:43], v[42:43]
	v_mov_b32_e32 v44, v22
	v_mov_b32_e32 v45, v26
	v_pk_fma_f32 v[40:41], v[40:41], v[40:41], v[42:43]
	v_mov_b32_e32 v42, v29
	v_pk_fma_f32 v[40:41], v[44:45], v[44:45], v[40:41]
	v_mov_b32_e32 v43, v33
	v_pk_fma_f32 v[40:41], v[46:47], v[46:47], v[40:41]
	v_pk_mul_f32 v[42:43], v[42:43], v[42:43]
	v_add_f32_e32 v1, v40, v41
	v_mov_b32_e32 v40, v28
	v_mov_b32_e32 v41, v32
	v_mov_b32_e32 v44, v30
	v_mov_b32_e32 v45, v34
	v_pk_fma_f32 v[40:41], v[40:41], v[40:41], v[42:43]
	v_mov_b32_e32 v46, v31
	v_mov_b32_e32 v47, v35
	v_pk_fma_f32 v[40:41], v[44:45], v[44:45], v[40:41]
	s_nop 0
	v_pk_fma_f32 v[40:41], v[46:47], v[46:47], v[40:41]
	s_nop 0
	v_add_f32_e32 v1, v40, v1
	v_add_f32_e32 v1, v1, v41
	v_mov_b32_e32 v40, v1
	s_nop 1
	v_permlane32_swap_b32_e32 v1, v40
	s_waitcnt lgkmcnt(0)
	v_add_f32_e32 v1, v1, v40
	v_mov_b32_e32 v40, v1
	s_nop 1
	v_permlane16_swap_b32_e32 v1, v40
	s_waitcnt lgkmcnt(0)
	v_add_f32_e32 v1, v1, v40
	s_nop 1
	v_mov_b32_dpp v40, v1 row_ror:8 row_mask:0xf bank_mask:0xf
	s_waitcnt lgkmcnt(0)
	v_add_f32_e32 v1, v1, v40
	s_nop 1
	v_mov_b32_dpp v40, v1 row_ror:4 row_mask:0xf bank_mask:0xf
	s_waitcnt lgkmcnt(0)
	v_add_f32_e32 v1, v1, v40
	s_nop 1
	v_mov_b32_dpp v40, v1 quad_perm:[2,3,0,1] row_mask:0xf bank_mask:0xf
	s_waitcnt lgkmcnt(0)
	v_add_f32_e32 v1, v1, v40
	s_nop 1
	v_mov_b32_dpp v40, v1 quad_perm:[1,0,3,2] row_mask:0xf bank_mask:0xf
	s_waitcnt lgkmcnt(0)
	v_add_f32_e32 v1, v1, v40
	v_fmamk_f32 v1, v1, 0x3a800000, v184
	v_mul_f32_e32 v40, 0x4b800000, v1
	v_cmp_gt_f32_e32 vcc, s33, v1
	s_nop 1
	v_cndmask_b32_e32 v1, v1, v40, vcc
	v_rsq_f32_e32 v1, v1
	s_nop 0
	v_mul_f32_e32 v40, 0x45800000, v1
	v_cndmask_b32_e32 v40, v1, v40, vcc
	v_pk_mul_f32 v[20:21], v[20:21], v[40:41] op_sel_hi:[1,0]
	v_pk_mul_f32 v[22:23], v[22:23], v[40:41] op_sel_hi:[1,0]
	v_pk_mul_f32 v[24:25], v[24:25], v[40:41] op_sel_hi:[1,0]
	v_pk_mul_f32 v[26:27], v[26:27], v[40:41] op_sel_hi:[1,0]
	s_waitcnt vmcnt(27)
	v_pk_mul_f32 v[20:21], v[114:115], v[20:21]
	v_pk_mul_f32 v[22:23], v[116:117], v[22:23]
	v_cvt_pk_bf16_f32 v20, v20, v21
	v_cvt_pk_bf16_f32 v21, v22, v23
	global_store_dwordx2 v[12:13], v[20:21], off
	s_nop 0
	v_cmp_lt_i32_e32 vcc, s64, v0
	s_or_b64 s[40:41], vcc, s[40:41]
	s_waitcnt vmcnt(26)
	v_pk_mul_f32 v[20:21], v[118:119], v[24:25]
	v_pk_mul_f32 v[22:23], v[120:121], v[26:27]
	v_cvt_pk_bf16_f32 v20, v20, v21
	v_cvt_pk_bf16_f32 v21, v22, v23
	global_store_dwordx2 v[12:13], v[20:21], off offset:512
	s_nop 0
	v_pk_mul_f32 v[24:25], v[28:29], v[40:41] op_sel_hi:[1,0]
	v_pk_mul_f32 v[26:27], v[30:31], v[40:41] op_sel_hi:[1,0]
	s_waitcnt vmcnt(25)
	v_pk_mul_f32 v[20:21], v[24:25], v[122:123]
	v_pk_mul_f32 v[22:23], v[26:27], v[124:125]
	v_cvt_pk_bf16_f32 v20, v20, v21
	v_cvt_pk_bf16_f32 v21, v22, v23
	global_store_dwordx2 v[12:13], v[20:21], off offset:1024
	s_nop 0
	v_pk_mul_f32 v[24:25], v[32:33], v[40:41] op_sel_hi:[1,0]
	v_pk_mul_f32 v[26:27], v[34:35], v[40:41] op_sel_hi:[1,0]
	s_waitcnt vmcnt(24)
	v_pk_mul_f32 v[20:21], v[24:25], v[126:127]
	v_pk_mul_f32 v[22:23], v[26:27], v[128:129]
	v_cvt_pk_bf16_f32 v20, v20, v21
	v_cvt_pk_bf16_f32 v21, v22, v23
	global_store_dwordx2 v[12:13], v[20:21], off offset:1536
	v_mov_b32_e32 v36, v114
	v_mov_b32_e32 v37, v115
	v_mov_b32_e32 v38, v116
	v_mov_b32_e32 v39, v117
	s_andn2_b64 exec, exec, s[40:41]
	s_cbranch_execnz .LBB0_880
.Lrnp_exit_1:
	s_waitcnt vmcnt(0)
.LBB0_881:
	s_or_b64 exec, exec, s[38:39]
	v_mov_b32_e32 v0, v185
	s_mov_b32 s4, s2
	s_cmpk_gt_i32 s4, 0x77f
	s_cbranch_scc1 .LBB0_899
	v_readlane_b32 s8, v255, 5
	v_readlane_b32 s10, v255, 7
	s_lshl_b32 s7, s4, 10
	v_readlane_b32 s9, v255, 6
	v_readlane_b32 s14, v255, 11
	s_add_i32 s7, s7, 0xffe30000
	s_lshl_b32 s10, s4, 2
	v_bfe_u32 v2, v0, 4, 1
	s_lshl_b32 s5, s4, 6
	s_lshl_b32 s6, s14, 6
	v_lshl_add_u32 v0, v0, 2, s7
	s_lshl_b32 s7, s14, 10
	s_lshl_b32 s8, s4, 4
	s_lshl_b32 s9, s14, 4
	s_add_i32 s10, s10, 0x7fffec00
	v_readlane_b32 s11, v255, 8
	v_readlane_b32 s12, v255, 9
	v_readlane_b32 s13, v255, 10
	v_readlane_b32 s15, v255, 12
	s_branch .LBB0_885
